# attention phase rewritten by hand: one MFMA-paced stream, softmax VALU in MFMA gaps, 4-slot LDS-DMA ring, conflict-free K swizzle, no half-wave exchange, q pre-scaled by scale*log2e
# speedup vs baseline: 1.0361x; 1.0361x over previous
.LBB0_276:
	s_or_b64 exec, exec, s[6:7]
	s_cmp_lg_u32 s8, 4
	s_cselect_b64 s[68:69], -1, 0
	s_cmp_eq_u32 s8, 4
	s_waitcnt lgkmcnt(0)
	s_barrier
	s_cselect_b32 s7, s21, s19
	s_cselect_b32 s6, s20, s18
	s_cselect_b32 s98, 1.0, 0x3e0293ee
	global_load_dwordx4 v[134:137], v205, s[6:7]
	s_waitcnt lgkmcnt(0)
	global_load_dwordx4 v[130:133], v205, s[6:7] offset:256
	s_lshl_b32 s43, s40, 8
	v_add_u32_e32 v172, s43, v161
	v_mov_b32_e32 v143, 0
	v_mov_b32_e32 v142, 1.0
	v_cmp_lt_i32_e64 s[6:7], s87, v172
	v_cmp_gt_i32_e32 vcc, s75, v172
	v_and_b32_e32 v158, 0xfcf, v172
	v_mov_b32_e32 v144, v142
	v_mov_b32_e32 v145, v143
	v_mov_b32_e32 v138, v142
	v_mov_b32_e32 v139, v143
	v_mov_b32_e32 v140, v142
	v_mov_b32_e32 v141, v143
	s_and_saveexec_b64 s[66:67], vcc
	s_cbranch_execz .LBB0_278
	v_lshrrev_b32_e32 v138, 6, v158
	v_cndmask_b32_e64 v138, v1, v138, s[4:5]
	v_lshl_or_b32 v138, v138, 8, v208
	global_load_dwordx4 v[142:145], v138, s[24:25]
	s_nop 0
	global_load_dwordx4 v[138:141], v138, s[24:25] offset:16

.LBB0_282:
	s_waitcnt lgkmcnt(0)
	v_mov_b32_e32 v170, v147
	v_mov_b32_e32 v171, v148
	v_mov_b32_e32 v147, v149
	v_pk_add_f32 v[146:147], v[170:171], v[146:147]
	s_add_i32 s45, 0, 0x20000
	v_add_f32_e32 v146, v146, v147
	v_fmamk_f32 v146, v146, 0x3c000000, v206
	v_rsq_f32_e32 v147, v146
	s_andn2_b64 vcc, exec, s[68:69]
	s_mov_b64 s[8:9], -1
	v_mul_f32_e32 v149, v128, v147
	s_waitcnt vmcnt(0)
	v_mul_f32_e32 v134, s98, v134
	v_mul_f32_e32 v135, s98, v135
	v_mul_f32_e32 v136, s98, v136
	v_mul_f32_e32 v137, s98, v137
	v_mul_f32_e32 v130, s98, v130
	v_mul_f32_e32 v131, s98, v131
	v_mul_f32_e32 v132, s98, v132
	v_mul_f32_e32 v133, s98, v133
	v_mul_f32_e32 v170, v135, v149
	v_mul_f32_e32 v149, v129, v147
	v_mul_f32_e32 v172, v131, v149
	v_mul_f32_e32 v149, v122, v147
	v_mul_f32_e32 v148, v127, v147
	v_mul_f32_e32 v210, v136, v149
	v_mul_f32_e32 v149, v123, v147
	v_mul_f32_e32 v146, v126, v147
	v_mul_f32_e32 v148, v130, v148
	v_mul_f32_e32 v212, v132, v149
	v_mul_f32_e32 v149, v124, v147
	v_mul_f32_e32 v146, v134, v146
	v_mul_f32_e32 v214, v137, v149
	v_mul_f32_e32 v147, v125, v147
	v_pk_mul_f32 v[148:149], v[142:143], v[148:149] op_sel:[1,0] op_sel_hi:[0,0]
	v_mul_f32_e32 v216, v133, v147
	v_pk_fma_f32 v[218:219], v[142:143], v[146:147], v[148:149] neg_lo:[0,0,1] neg_hi:[0,0,1]
	v_pk_fma_f32 v[146:147], v[142:143], v[146:147], v[148:149] op_sel_hi:[1,0,1]
	v_pk_mul_f32 v[148:149], v[144:145], v[172:173] op_sel:[1,0] op_sel_hi:[0,0]
	v_pk_fma_f32 v[172:173], v[144:145], v[170:171], v[148:149] neg_lo:[0,0,1] neg_hi:[0,0,1]
	v_pk_fma_f32 v[148:149], v[144:145], v[170:171], v[148:149] op_sel_hi:[1,0,1]
	v_cvt_pk_bf16_f32 v146, v218, v147
	v_cvt_pk_bf16_f32 v147, v172, v149
	v_pk_mul_f32 v[148:149], v[138:139], v[212:213] op_sel:[1,0] op_sel_hi:[0,0]
	v_pk_fma_f32 v[170:171], v[138:139], v[210:211], v[148:149] neg_lo:[0,0,1] neg_hi:[0,0,1]
	v_pk_fma_f32 v[148:149], v[138:139], v[210:211], v[148:149] op_sel_hi:[1,0,1]
	s_nop 0
	v_cvt_pk_bf16_f32 v148, v170, v149
	v_pk_mul_f32 v[170:171], v[140:141], v[216:217] op_sel:[1,0] op_sel_hi:[0,0]
	v_pk_fma_f32 v[172:173], v[140:141], v[214:215], v[170:171] neg_lo:[0,0,1] neg_hi:[0,0,1]
	v_pk_fma_f32 v[170:171], v[140:141], v[214:215], v[170:171] op_sel_hi:[1,0,1]
	v_mov_b32_e32 v173, v159
	v_cvt_pk_bf16_f32 v149, v172, v171
	v_lshlrev_b32_e32 v172, 1, v160
	v_lshl_add_u64 v[170:171], v[176:177], 0, v[172:173]
	global_store_dwordx4 v[170:171], v[146:149], off
	v_cndmask_b32_e64 v170, 0, 1, s[68:69]
	v_cmp_ne_u32_e64 s[6:7], 1, v170
	v_add_u32_e32 v146, s45, v181
	ds_read_b128 v[146:149], v146 offset:16
	s_cbranch_vccnz .LBB0_284
	s_ashr_i32 s67, s66, 31
	v_lshl_add_u64 v[170:171], s[66:67], 1, v[174:175]
	v_lshl_add_u64 v[176:177], v[170:171], 0, s[38:39]
	s_mov_b64 s[8:9], 0

.LBB0_419:
	s_ashr_i32 s6, s3, 7
	s_lshl_b32 s1, s3, 8
	s_lshl_b32 s0, s6, 12
	s_and_b32 s1, s1, 0xf00
	s_bfe_u32 s18, s3, 0x10006
	s_or_b32 s0, s0, s1
	s_lshl_b32 s44, s3, 3
	s_ashr_i32 s1, s0, 31
	s_lshl_b32 s19, s18, 9
	s_and_b32 s44, s44, 0x180
	s_lshl_b64 s[0:1], s[0:1], 10
	s_or_b32 s19, s19, s44
	s_or_b32 s0, s0, s19
	s_lshl_b32 s6, s6, 1
	s_or_b32 s18, s6, s18
	s_lshl_b64 s[0:1], s[0:1], 1
	s_add_u32 s60, s25, s0
	s_addc_u32 s61, s28, s1
	s_mul_hi_i32 s19, s18, 0x110000
	s_mul_i32 s18, s18, 0x110000
	s_add_u32 s62, s9, s18
	s_addc_u32 s63, s20, s19
	s_add_u32 s64, s29, s18
	s_addc_u32 s65, s30, s19
	v_readfirstlane_b32 s44, v1
	s_lshr_b32 s6, s44, 6
	s_lshl_b32 s45, s6, 10
	s_lshl_b32 s44, s6, 8
	s_add_i32 s44, s44, 0x20000
	s_lshl_b32 s6, s6, 5
	v_lshrrev_b32_e32 v131, 4, v1
	v_xor_b32_e32 v132, v1, v131
	v_and_b32_e32 v132, 15, v132
	v_lshlrev_b32_e32 v132, 4, v132
	v_lshl_or_b32 v146, v131, 8, v132
	v_add_u32_e32 v150, 0x2000, v146
	v_and_b32_e32 v131, 15, v144
	v_lshlrev_b32_e32 v131, 4, v131
	v_lshlrev_b32_e32 v132, 8, v144
	v_add_u32_e32 v133, 0, v182
	v_xad_u32 v183, v133, v131, v132
	v_add_u32_e32 v133, 32, v182
	v_xad_u32 v184, v133, v131, v132
	v_add_u32_e32 v133, 64, v182
	v_xad_u32 v185, v133, v131, v132
	v_add_u32_e32 v133, 96, v182
	v_xad_u32 v186, v133, v131, v132
	v_add_u32_e32 v133, 128, v182
	v_xad_u32 v187, v133, v131, v132
	v_add_u32_e32 v133, 160, v182
	v_xad_u32 v188, v133, v131, v132
	v_add_u32_e32 v133, 192, v182
	v_xad_u32 v189, v133, v131, v132
	v_add_u32_e32 v133, 224, v182
	v_xad_u32 v190, v133, v131, v132
	v_bfe_u32 v131, v1, 7, 2
	v_lshlrev_b32_e32 v131, 11, v131
	v_bfe_u32 v132, v1, 2, 3
	v_lshl_or_b32 v131, v132, 8, v131
	v_bfe_u32 v132, v1, 5, 2
	v_lshl_or_b32 v131, v132, 6, v131
	v_and_b32_e32 v132, 3, v1
	v_lshl_or_b32 v148, v132, 4, v131
	v_add_u32_e32 v152, 0x2000, v148
	s_add_i32 m0, s45, 0x0
	s_nop 0
	global_load_lds_dwordx4 v148, s[64:65]
	s_add_i32 m0, s45, 0x4000
	s_nop 0
	global_load_lds_dwordx4 v146, s[62:63]
	s_add_i32 m0, s45, 0x2000
	s_nop 0
	global_load_lds_dwordx4 v152, s[64:65]
	s_add_i32 m0, s45, 0x6000
	s_nop 0
	global_load_lds_dwordx4 v150, s[62:63]
	s_add_u32 s62, s62, 0x4000
	s_addc_u32 s63, s63, 0
	s_add_u32 s64, s64, 0x4000
	s_addc_u32 s65, s65, 0
	s_add_i32 m0, s45, 0x8000
	s_nop 0
	global_load_lds_dwordx4 v148, s[64:65]
	s_add_i32 m0, s45, 0xc000
	s_nop 0
	global_load_lds_dwordx4 v146, s[62:63]
	s_add_i32 m0, s45, 0xa000
	s_nop 0
	global_load_lds_dwordx4 v152, s[64:65]
	s_add_i32 m0, s45, 0xe000
	s_nop 0
	global_load_lds_dwordx4 v150, s[62:63]
	s_add_u32 s62, s62, 0x4000
	s_addc_u32 s63, s63, 0
	s_add_u32 s64, s64, 0x4000
	s_addc_u32 s65, s65, 0
	v_mov_b32_e32 v165, v155
	v_or_b32_e32 v2, s6, v144
	v_mov_b32_e32 v3, v155
	v_lshlrev_b64 v[2:3], 11, v[2:3]
	v_lshl_add_u64 v[2:3], s[60:61], 0, v[2:3]
	v_lshl_add_u64 v[2:3], v[2:3], 0, v[164:165]
	global_load_dwordx4 v[106:109], v[2:3], off
	global_load_dwordx4 v[102:105], v[2:3], off offset:32
	global_load_dwordx4 v[98:101], v[2:3], off offset:64
	global_load_dwordx4 v[126:129], v[2:3], off offset:96
	global_load_dwordx4 v[122:125], v[2:3], off offset:128
	global_load_dwordx4 v[118:121], v[2:3], off offset:160
	global_load_dwordx4 v[114:117], v[2:3], off offset:192
	global_load_dwordx4 v[110:113], v[2:3], off offset:224
	v_add_u32_e32 v240, 0x10000, v183
	v_add_u32_e32 v241, 0x10000, v184
	v_add_u32_e32 v242, 0x10000, v185
	v_add_u32_e32 v243, 0x10000, v186
	v_add_u32_e32 v244, 0x10000, v187
	v_add_u32_e32 v245, 0x10000, v188
	v_add_u32_e32 v246, 0x10000, v189
	v_add_u32_e32 v247, 0x10000, v190
	v_add_u32_e32 v130, 0x10000, v145
	v_mov_b32_e32 v2, 0
	v_mov_b32_e32 v3, 0
	v_mov_b32_e32 v4, 0
	v_mov_b32_e32 v5, 0
	v_mov_b32_e32 v6, 0
	v_mov_b32_e32 v7, 0
	v_mov_b32_e32 v8, 0
	v_mov_b32_e32 v9, 0
	v_mov_b32_e32 v10, 0
	v_mov_b32_e32 v11, 0
	v_mov_b32_e32 v12, 0
	v_mov_b32_e32 v13, 0
	v_mov_b32_e32 v14, 0
	v_mov_b32_e32 v15, 0
	v_mov_b32_e32 v16, 0
	v_mov_b32_e32 v17, 0
	v_mov_b32_e32 v18, 0
	v_mov_b32_e32 v19, 0
	v_mov_b32_e32 v20, 0
	v_mov_b32_e32 v21, 0
	v_mov_b32_e32 v22, 0
	v_mov_b32_e32 v23, 0
	v_mov_b32_e32 v24, 0
	v_mov_b32_e32 v25, 0
	v_mov_b32_e32 v26, 0
	v_mov_b32_e32 v27, 0
	v_mov_b32_e32 v28, 0
	v_mov_b32_e32 v29, 0
	v_mov_b32_e32 v30, 0
	v_mov_b32_e32 v31, 0
	v_mov_b32_e32 v32, 0
	v_mov_b32_e32 v33, 0
	v_mov_b32_e32 v34, 0
	v_mov_b32_e32 v35, 0
	v_mov_b32_e32 v36, 0
	v_mov_b32_e32 v37, 0
	v_mov_b32_e32 v38, 0
	v_mov_b32_e32 v39, 0
	v_mov_b32_e32 v40, 0
	v_mov_b32_e32 v41, 0
	v_mov_b32_e32 v42, 0
	v_mov_b32_e32 v43, 0
	v_mov_b32_e32 v44, 0
	v_mov_b32_e32 v45, 0
	v_mov_b32_e32 v46, 0
	v_mov_b32_e32 v47, 0
	v_mov_b32_e32 v48, 0
	v_mov_b32_e32 v49, 0
	v_mov_b32_e32 v50, 0
	v_mov_b32_e32 v51, 0
	v_mov_b32_e32 v52, 0
	v_mov_b32_e32 v53, 0
	v_mov_b32_e32 v54, 0
	v_mov_b32_e32 v55, 0
	v_mov_b32_e32 v56, 0
	v_mov_b32_e32 v57, 0
	v_mov_b32_e32 v58, 0
	v_mov_b32_e32 v59, 0
	v_mov_b32_e32 v60, 0
	v_mov_b32_e32 v61, 0
	v_mov_b32_e32 v62, 0
	v_mov_b32_e32 v63, 0
	v_mov_b32_e32 v64, 0
	v_mov_b32_e32 v65, 0
	s_waitcnt vmcnt(0)
	s_barrier
	ds_read_b128 v[166:169], v183 offset:16384
	ds_read_b128 v[170:173], v183 offset:24576
	ds_read_b128 v[174:177], v184 offset:16384
	ds_read_b128 v[178:181], v184 offset:24576
	ds_read_b128 v[224:227], v185 offset:16384
	ds_read_b128 v[228:231], v185 offset:24576
	ds_read_b128 v[232:235], v186 offset:16384
	ds_read_b128 v[236:239], v186 offset:24576
	s_waitcnt lgkmcnt(7)
	v_mfma_f32_32x32x16_bf16 v[66:81], v[166:169], v[106:109], 0
	s_add_i32 m0, s45, 0x10000
	s_nop 0
	global_load_lds_dwordx4 v148, s[64:65]
	s_waitcnt lgkmcnt(6)
	v_mfma_f32_32x32x16_bf16 v[82:97], v[170:173], v[106:109], 0
	s_add_i32 m0, s45, 0x14000
	s_nop 0
	global_load_lds_dwordx4 v146, s[62:63]
	ds_read_b128 v[166:169], v187 offset:16384
	ds_read_b128 v[170:173], v187 offset:24576
	s_waitcnt lgkmcnt(7)
	v_mfma_f32_32x32x16_bf16 v[66:81], v[174:177], v[102:105], v[66:81]
	s_add_i32 m0, s45, 0x12000
	s_nop 0
	global_load_lds_dwordx4 v152, s[64:65]
	s_waitcnt lgkmcnt(6)
	v_mfma_f32_32x32x16_bf16 v[82:97], v[178:181], v[102:105], v[82:97]
	s_add_i32 m0, s45, 0x16000
	s_nop 0
	global_load_lds_dwordx4 v150, s[62:63]
	s_add_u32 s62, s62, 0x4000
	s_addc_u32 s63, s63, 0
	s_add_u32 s64, s64, 0x4000
	s_addc_u32 s65, s65, 0
	ds_read_b128 v[174:177], v188 offset:16384
	ds_read_b128 v[178:181], v188 offset:24576
	s_waitcnt lgkmcnt(7)
	v_mfma_f32_32x32x16_bf16 v[66:81], v[224:227], v[98:101], v[66:81]
	s_waitcnt lgkmcnt(6)
	v_mfma_f32_32x32x16_bf16 v[82:97], v[228:231], v[98:101], v[82:97]
	ds_read_b128 v[224:227], v189 offset:16384
	ds_read_b128 v[228:231], v189 offset:24576
	s_waitcnt lgkmcnt(7)
	v_mfma_f32_32x32x16_bf16 v[66:81], v[232:235], v[126:129], v[66:81]
	s_waitcnt lgkmcnt(6)
	v_mfma_f32_32x32x16_bf16 v[82:97], v[236:239], v[126:129], v[82:97]
	ds_read_b128 v[232:235], v190 offset:16384
	ds_read_b128 v[236:239], v190 offset:24576
	s_waitcnt lgkmcnt(7)
	v_mfma_f32_32x32x16_bf16 v[66:81], v[166:169], v[122:125], v[66:81]
	s_waitcnt lgkmcnt(6)
	v_mfma_f32_32x32x16_bf16 v[82:97], v[170:173], v[122:125], v[82:97]
	s_waitcnt lgkmcnt(5)
	v_mfma_f32_32x32x16_bf16 v[66:81], v[174:177], v[118:121], v[66:81]
	s_waitcnt lgkmcnt(4)
	v_mfma_f32_32x32x16_bf16 v[82:97], v[178:181], v[118:121], v[82:97]
	s_waitcnt lgkmcnt(3)
	v_mfma_f32_32x32x16_bf16 v[66:81], v[224:227], v[114:117], v[66:81]
	s_waitcnt lgkmcnt(2)
	v_mfma_f32_32x32x16_bf16 v[82:97], v[228:231], v[114:117], v[82:97]
	s_waitcnt lgkmcnt(1)
	v_mfma_f32_32x32x16_bf16 v[66:81], v[232:235], v[110:113], v[66:81]
	s_waitcnt lgkmcnt(0)
	v_mfma_f32_32x32x16_bf16 v[82:97], v[236:239], v[110:113], v[82:97]
	s_nop 7
	s_nop 7
	v_exp_f32_e32 v66, v66
	v_exp_f32_e32 v67, v67
	v_exp_f32_e32 v68, v68
	v_exp_f32_e32 v69, v69
	v_exp_f32_e32 v70, v70
	v_exp_f32_e32 v71, v71
	v_exp_f32_e32 v72, v72
	v_exp_f32_e32 v73, v73
	v_exp_f32_e32 v74, v74
	v_exp_f32_e32 v75, v75
	v_exp_f32_e32 v76, v76
	v_exp_f32_e32 v77, v77
	v_exp_f32_e32 v78, v78
	v_exp_f32_e32 v79, v79
	v_exp_f32_e32 v80, v80
	v_exp_f32_e32 v81, v81
	v_exp_f32_e32 v82, v82
	v_exp_f32_e32 v83, v83
	v_exp_f32_e32 v84, v84
	v_exp_f32_e32 v85, v85
	v_exp_f32_e32 v86, v86
	v_exp_f32_e32 v87, v87
	v_exp_f32_e32 v88, v88
	v_exp_f32_e32 v89, v89
	v_exp_f32_e32 v90, v90
	v_exp_f32_e32 v91, v91
	v_exp_f32_e32 v92, v92
	v_exp_f32_e32 v93, v93
	v_exp_f32_e32 v94, v94
	v_exp_f32_e32 v95, v95
	v_exp_f32_e32 v96, v96
	v_exp_f32_e32 v97, v97
	ds_read_b128 v[166:169], v183 offset:49152
	ds_read_b128 v[170:173], v183 offset:57344
	ds_read_b128 v[174:177], v184 offset:49152
	ds_read_b128 v[178:181], v184 offset:57344
	ds_read_b128 v[224:227], v185 offset:49152
	ds_read_b128 v[228:231], v185 offset:57344
	ds_read_b128 v[232:235], v186 offset:49152
	ds_read_b128 v[236:239], v186 offset:57344
	s_waitcnt vmcnt(0)
	s_barrier
	s_mov_b32 s66, 16
.Lattn_loop:
	s_waitcnt lgkmcnt(7)
	v_mfma_f32_32x32x16_bf16 v[192:207], v[166:169], v[106:109], 0
	s_add_i32 m0, s45, 0x18000
	v_add_f32_e32 v131, v66, v67
	v_add_f32_e32 v132, v68, v69
	v_add_f32_e32 v131, v70, v131
	global_load_lds_dwordx4 v148, s[64:65]
	s_waitcnt lgkmcnt(6)
	v_mfma_f32_32x32x16_bf16 v[208:223], v[170:173], v[106:109], 0
	s_add_i32 m0, s45, 0x1c000
	v_add_f32_e32 v132, v71, v132
	v_add_f32_e32 v131, v72, v131
	v_add_f32_e32 v132, v73, v132
	global_load_lds_dwordx4 v146, s[62:63]
	ds_read_b128 v[166:169], v187 offset:49152
	ds_read_b128 v[170:173], v187 offset:57344
	s_waitcnt lgkmcnt(7)
	v_mfma_f32_32x32x16_bf16 v[192:207], v[174:177], v[102:105], v[192:207]
	s_add_i32 m0, s45, 0x1a000
	v_add_f32_e32 v131, v74, v131
	v_add_f32_e32 v132, v75, v132
	v_add_f32_e32 v131, v76, v131
	global_load_lds_dwordx4 v152, s[64:65]
	s_waitcnt lgkmcnt(6)
	v_mfma_f32_32x32x16_bf16 v[208:223], v[178:181], v[102:105], v[208:223]
	s_add_i32 m0, s45, 0x1e000
	v_add_f32_e32 v132, v77, v132
	v_add_f32_e32 v131, v78, v131
	v_add_f32_e32 v132, v79, v132
	global_load_lds_dwordx4 v150, s[62:63]
	s_add_u32 s62, s62, 0x4000
	s_addc_u32 s63, s63, 0
	s_add_u32 s64, s64, 0x4000
	s_addc_u32 s65, s65, 0
	ds_read_b128 v[174:177], v188 offset:49152
	ds_read_b128 v[178:181], v188 offset:57344
	s_waitcnt lgkmcnt(7)
	v_mfma_f32_32x32x16_bf16 v[192:207], v[224:227], v[98:101], v[192:207]
	v_add_f32_e32 v131, v80, v131
	v_add_f32_e32 v132, v81, v132
	v_add_f32_e32 v131, v82, v131
	s_waitcnt lgkmcnt(6)
	v_mfma_f32_32x32x16_bf16 v[208:223], v[228:231], v[98:101], v[208:223]
	v_add_f32_e32 v132, v83, v132
	v_add_f32_e32 v131, v84, v131
	v_add_f32_e32 v132, v85, v132
	ds_read_b128 v[224:227], v189 offset:49152
	ds_read_b128 v[228:231], v189 offset:57344
	s_waitcnt lgkmcnt(7)
	v_mfma_f32_32x32x16_bf16 v[192:207], v[232:235], v[126:129], v[192:207]
	v_add_f32_e32 v131, v86, v131
	v_add_f32_e32 v132, v87, v132
	v_add_f32_e32 v131, v88, v131
	s_waitcnt lgkmcnt(6)
	v_mfma_f32_32x32x16_bf16 v[208:223], v[236:239], v[126:129], v[208:223]
	v_add_f32_e32 v132, v89, v132
	v_add_f32_e32 v131, v90, v131
	v_add_f32_e32 v132, v91, v132
	ds_read_b128 v[232:235], v190 offset:49152
	ds_read_b128 v[236:239], v190 offset:57344
	s_waitcnt lgkmcnt(7)
	v_mfma_f32_32x32x16_bf16 v[192:207], v[166:169], v[122:125], v[192:207]
	v_add_f32_e32 v131, v92, v131
	v_add_f32_e32 v132, v93, v132
	v_add_f32_e32 v131, v94, v131
	s_waitcnt lgkmcnt(6)
	v_mfma_f32_32x32x16_bf16 v[208:223], v[170:173], v[122:125], v[208:223]
	v_add_f32_e32 v132, v95, v132
	v_add_f32_e32 v131, v96, v131
	v_add_f32_e32 v132, v97, v132
	ds_read_b64_tr_b16 v[166:167], v145 offset:0
	ds_read_b64_tr_b16 v[168:169], v145 offset:2048
	ds_read_b64_tr_b16 v[170:171], v145 offset:4096
	ds_read_b64_tr_b16 v[172:173], v145 offset:6144
	s_waitcnt lgkmcnt(9)
	v_mfma_f32_32x32x16_bf16 v[192:207], v[174:177], v[118:121], v[192:207]
	v_add_f32_e32 v131, v131, v132
	v_add_f32_e32 v165, v165, v131
	v_cvt_pk_bf16_f32 v66, v66, v67
	s_waitcnt lgkmcnt(8)
	v_mfma_f32_32x32x16_bf16 v[208:223], v[178:181], v[118:121], v[208:223]
	v_cvt_pk_bf16_f32 v67, v68, v69
	v_cvt_pk_bf16_f32 v68, v70, v71
	v_cvt_pk_bf16_f32 v69, v72, v73
	ds_read_b64_tr_b16 v[174:175], v145 offset:8192
	ds_read_b64_tr_b16 v[176:177], v145 offset:10240
	ds_read_b64_tr_b16 v[178:179], v145 offset:12288
	ds_read_b64_tr_b16 v[180:181], v145 offset:14336
	s_waitcnt lgkmcnt(11)
	v_mfma_f32_32x32x16_bf16 v[192:207], v[224:227], v[114:117], v[192:207]
	v_cvt_pk_bf16_f32 v74, v74, v75
	v_cvt_pk_bf16_f32 v75, v76, v77
	v_cvt_pk_bf16_f32 v76, v78, v79
	s_waitcnt lgkmcnt(10)
	v_mfma_f32_32x32x16_bf16 v[208:223], v[228:231], v[114:117], v[208:223]
	v_cvt_pk_bf16_f32 v77, v80, v81
	v_cvt_pk_bf16_f32 v82, v82, v83
	v_cvt_pk_bf16_f32 v83, v84, v85
	ds_read_b64_tr_b16 v[224:225], v145 offset:512
	ds_read_b64_tr_b16 v[226:227], v145 offset:2560
	ds_read_b64_tr_b16 v[228:229], v145 offset:4608
	ds_read_b64_tr_b16 v[230:231], v145 offset:6656
	s_waitcnt lgkmcnt(13)
	v_mfma_f32_32x32x16_bf16 v[192:207], v[232:235], v[110:113], v[192:207]
	v_cvt_pk_bf16_f32 v84, v86, v87
	v_cvt_pk_bf16_f32 v85, v88, v89
	v_cvt_pk_bf16_f32 v90, v90, v91
	s_waitcnt lgkmcnt(12)
	v_mfma_f32_32x32x16_bf16 v[208:223], v[236:239], v[110:113], v[208:223]
	v_cvt_pk_bf16_f32 v91, v92, v93
	v_cvt_pk_bf16_f32 v92, v94, v95
	v_cvt_pk_bf16_f32 v93, v96, v97
	s_waitcnt lgkmcnt(10)
	v_mfma_f32_32x32x16_bf16 v[2:17], v[66:69], v[166:169], v[2:17]
	ds_read_b64_tr_b16 v[232:233], v145 offset:8704
	ds_read_b64_tr_b16 v[234:235], v145 offset:10752
	s_waitcnt lgkmcnt(10)
	v_mfma_f32_32x32x16_bf16 v[2:17], v[74:77], v[170:173], v[2:17]
	ds_read_b64_tr_b16 v[236:237], v145 offset:12800
	ds_read_b64_tr_b16 v[238:239], v145 offset:14848
	s_waitcnt lgkmcnt(10)
	v_mfma_f32_32x32x16_bf16 v[2:17], v[82:85], v[174:177], v[2:17]
	ds_read_b64_tr_b16 v[166:167], v145 offset:1024
	ds_read_b64_tr_b16 v[168:169], v145 offset:3072
	s_waitcnt lgkmcnt(10)
	v_mfma_f32_32x32x16_bf16 v[2:17], v[90:93], v[178:181], v[2:17]
	ds_read_b64_tr_b16 v[170:171], v145 offset:5120
	ds_read_b64_tr_b16 v[172:173], v145 offset:7168
	v_exp_f32_e32 v192, v192
	v_exp_f32_e32 v193, v193
	v_exp_f32_e32 v194, v194
	s_waitcnt lgkmcnt(10)
	v_mfma_f32_32x32x16_bf16 v[18:33], v[66:69], v[224:227], v[18:33]
	ds_read_b64_tr_b16 v[174:175], v145 offset:9216
	ds_read_b64_tr_b16 v[176:177], v145 offset:11264
	v_exp_f32_e32 v195, v195
	v_exp_f32_e32 v196, v196
	s_waitcnt lgkmcnt(10)
	v_mfma_f32_32x32x16_bf16 v[18:33], v[74:77], v[228:231], v[18:33]
	ds_read_b64_tr_b16 v[178:179], v145 offset:13312
	ds_read_b64_tr_b16 v[180:181], v145 offset:15360
	v_exp_f32_e32 v197, v197
	v_exp_f32_e32 v198, v198
	v_exp_f32_e32 v199, v199
	s_waitcnt lgkmcnt(10)
	v_mfma_f32_32x32x16_bf16 v[18:33], v[82:85], v[232:235], v[18:33]
	ds_read_b64_tr_b16 v[224:225], v145 offset:1536
	ds_read_b64_tr_b16 v[226:227], v145 offset:3584
	v_exp_f32_e32 v200, v200
	v_exp_f32_e32 v201, v201
	s_waitcnt lgkmcnt(10)
	v_mfma_f32_32x32x16_bf16 v[18:33], v[90:93], v[236:239], v[18:33]
	ds_read_b64_tr_b16 v[228:229], v145 offset:5632
	ds_read_b64_tr_b16 v[230:231], v145 offset:7680
	v_exp_f32_e32 v202, v202
	v_exp_f32_e32 v203, v203
	v_exp_f32_e32 v204, v204
	s_waitcnt lgkmcnt(10)
	v_mfma_f32_32x32x16_bf16 v[34:49], v[66:69], v[166:169], v[34:49]
	ds_read_b64_tr_b16 v[232:233], v145 offset:9728
	ds_read_b64_tr_b16 v[234:235], v145 offset:11776
	ds_read_b128 v[166:169], v240 offset:16384
	v_exp_f32_e32 v205, v205
	v_exp_f32_e32 v206, v206
	s_waitcnt lgkmcnt(11)
	v_mfma_f32_32x32x16_bf16 v[34:49], v[74:77], v[170:173], v[34:49]
	ds_read_b64_tr_b16 v[236:237], v145 offset:13824
	ds_read_b64_tr_b16 v[238:239], v145 offset:15872
	ds_read_b128 v[170:173], v240 offset:24576
	v_exp_f32_e32 v207, v207
	v_exp_f32_e32 v208, v208
	v_exp_f32_e32 v209, v209
	s_waitcnt lgkmcnt(12)
	v_mfma_f32_32x32x16_bf16 v[34:49], v[82:85], v[174:177], v[34:49]
	ds_read_b128 v[174:177], v241 offset:16384
	v_exp_f32_e32 v210, v210
	v_exp_f32_e32 v211, v211
	s_waitcnt lgkmcnt(11)
	v_mfma_f32_32x32x16_bf16 v[34:49], v[90:93], v[178:181], v[34:49]
	ds_read_b128 v[178:181], v241 offset:24576
	v_exp_f32_e32 v212, v212
	v_exp_f32_e32 v213, v213
	v_exp_f32_e32 v214, v214
	s_waitcnt lgkmcnt(10)
	v_mfma_f32_32x32x16_bf16 v[50:65], v[66:69], v[224:227], v[50:65]
	ds_read_b128 v[224:227], v242 offset:16384
	v_exp_f32_e32 v215, v215
	v_exp_f32_e32 v216, v216
	s_waitcnt lgkmcnt(9)
	v_mfma_f32_32x32x16_bf16 v[50:65], v[74:77], v[228:231], v[50:65]
	ds_read_b128 v[228:231], v242 offset:24576
	v_exp_f32_e32 v217, v217
	v_exp_f32_e32 v218, v218
	v_exp_f32_e32 v219, v219
	s_waitcnt lgkmcnt(8)
	v_mfma_f32_32x32x16_bf16 v[50:65], v[82:85], v[232:235], v[50:65]
	ds_read_b128 v[232:235], v243 offset:16384
	v_exp_f32_e32 v220, v220
	v_exp_f32_e32 v221, v221
	s_waitcnt lgkmcnt(6)
	v_mfma_f32_32x32x16_bf16 v[50:65], v[90:93], v[236:239], v[50:65]
	ds_read_b128 v[236:239], v243 offset:24576
	v_exp_f32_e32 v222, v222
	v_exp_f32_e32 v223, v223
	s_waitcnt vmcnt(0)
	s_barrier
	v_mfma_f32_32x32x16_bf16 v[66:81], v[166:169], v[106:109], 0
	s_add_i32 m0, s45, 0x0
	v_add_f32_e32 v131, v192, v193
	v_add_f32_e32 v132, v194, v195
	v_add_f32_e32 v131, v196, v131
	global_load_lds_dwordx4 v148, s[64:65]
	s_waitcnt lgkmcnt(6)
	v_mfma_f32_32x32x16_bf16 v[82:97], v[170:173], v[106:109], 0
	s_add_i32 m0, s45, 0x4000
	v_add_f32_e32 v132, v197, v132
	v_add_f32_e32 v131, v198, v131
	v_add_f32_e32 v132, v199, v132
	global_load_lds_dwordx4 v146, s[62:63]
	ds_read_b128 v[166:169], v244 offset:16384
	ds_read_b128 v[170:173], v244 offset:24576
	s_waitcnt lgkmcnt(7)
	v_mfma_f32_32x32x16_bf16 v[66:81], v[174:177], v[102:105], v[66:81]
	s_add_i32 m0, s45, 0x2000
	v_add_f32_e32 v131, v200, v131
	v_add_f32_e32 v132, v201, v132
	v_add_f32_e32 v131, v202, v131
	global_load_lds_dwordx4 v152, s[64:65]
	s_waitcnt lgkmcnt(6)
	v_mfma_f32_32x32x16_bf16 v[82:97], v[178:181], v[102:105], v[82:97]
	s_add_i32 m0, s45, 0x6000
	v_add_f32_e32 v132, v203, v132
	v_add_f32_e32 v131, v204, v131
	v_add_f32_e32 v132, v205, v132
	global_load_lds_dwordx4 v150, s[62:63]
	s_add_u32 s62, s62, 0x4000
	s_addc_u32 s63, s63, 0
	s_add_u32 s64, s64, 0x4000
	s_addc_u32 s65, s65, 0
	ds_read_b128 v[174:177], v245 offset:16384
	ds_read_b128 v[178:181], v245 offset:24576
	s_waitcnt lgkmcnt(7)
	v_mfma_f32_32x32x16_bf16 v[66:81], v[224:227], v[98:101], v[66:81]
	v_add_f32_e32 v131, v206, v131
	v_add_f32_e32 v132, v207, v132
	v_add_f32_e32 v131, v208, v131
	s_waitcnt lgkmcnt(6)
	v_mfma_f32_32x32x16_bf16 v[82:97], v[228:231], v[98:101], v[82:97]
	v_add_f32_e32 v132, v209, v132
	v_add_f32_e32 v131, v210, v131
	v_add_f32_e32 v132, v211, v132
	ds_read_b128 v[224:227], v246 offset:16384
	ds_read_b128 v[228:231], v246 offset:24576
	s_waitcnt lgkmcnt(7)
	v_mfma_f32_32x32x16_bf16 v[66:81], v[232:235], v[126:129], v[66:81]
	v_add_f32_e32 v131, v212, v131
	v_add_f32_e32 v132, v213, v132
	v_add_f32_e32 v131, v214, v131
	s_waitcnt lgkmcnt(6)
	v_mfma_f32_32x32x16_bf16 v[82:97], v[236:239], v[126:129], v[82:97]
	v_add_f32_e32 v132, v215, v132
	v_add_f32_e32 v131, v216, v131
	v_add_f32_e32 v132, v217, v132
	ds_read_b128 v[232:235], v247 offset:16384
	ds_read_b128 v[236:239], v247 offset:24576
	s_waitcnt lgkmcnt(7)
	v_mfma_f32_32x32x16_bf16 v[66:81], v[166:169], v[122:125], v[66:81]
	v_add_f32_e32 v131, v218, v131
	v_add_f32_e32 v132, v219, v132
	v_add_f32_e32 v131, v220, v131
	s_waitcnt lgkmcnt(6)
	v_mfma_f32_32x32x16_bf16 v[82:97], v[170:173], v[122:125], v[82:97]
	v_add_f32_e32 v132, v221, v132
	v_add_f32_e32 v131, v222, v131
	v_add_f32_e32 v132, v223, v132
	ds_read_b64_tr_b16 v[166:167], v145 offset:32768
	ds_read_b64_tr_b16 v[168:169], v145 offset:34816
	ds_read_b64_tr_b16 v[170:171], v145 offset:36864
	ds_read_b64_tr_b16 v[172:173], v145 offset:38912
	s_waitcnt lgkmcnt(9)
	v_mfma_f32_32x32x16_bf16 v[66:81], v[174:177], v[118:121], v[66:81]
	v_add_f32_e32 v131, v131, v132
	v_add_f32_e32 v165, v165, v131
	v_cvt_pk_bf16_f32 v192, v192, v193
	s_waitcnt lgkmcnt(8)
	v_mfma_f32_32x32x16_bf16 v[82:97], v[178:181], v[118:121], v[82:97]
	v_cvt_pk_bf16_f32 v193, v194, v195
	v_cvt_pk_bf16_f32 v194, v196, v197
	v_cvt_pk_bf16_f32 v195, v198, v199
	ds_read_b64_tr_b16 v[174:175], v145 offset:40960
	ds_read_b64_tr_b16 v[176:177], v145 offset:43008
	ds_read_b64_tr_b16 v[178:179], v145 offset:45056
	ds_read_b64_tr_b16 v[180:181], v145 offset:47104
	s_waitcnt lgkmcnt(11)
	v_mfma_f32_32x32x16_bf16 v[66:81], v[224:227], v[114:117], v[66:81]
	v_cvt_pk_bf16_f32 v200, v200, v201
	v_cvt_pk_bf16_f32 v201, v202, v203
	v_cvt_pk_bf16_f32 v202, v204, v205
	s_waitcnt lgkmcnt(10)
	v_mfma_f32_32x32x16_bf16 v[82:97], v[228:231], v[114:117], v[82:97]
	v_cvt_pk_bf16_f32 v203, v206, v207
	v_cvt_pk_bf16_f32 v208, v208, v209
	v_cvt_pk_bf16_f32 v209, v210, v211
	ds_read_b64_tr_b16 v[224:225], v145 offset:33280
	ds_read_b64_tr_b16 v[226:227], v145 offset:35328
	ds_read_b64_tr_b16 v[228:229], v145 offset:37376
	ds_read_b64_tr_b16 v[230:231], v145 offset:39424
	s_waitcnt lgkmcnt(13)
	v_mfma_f32_32x32x16_bf16 v[66:81], v[232:235], v[110:113], v[66:81]
	v_cvt_pk_bf16_f32 v210, v212, v213
	v_cvt_pk_bf16_f32 v211, v214, v215
	v_cvt_pk_bf16_f32 v216, v216, v217
	s_waitcnt lgkmcnt(12)
	v_mfma_f32_32x32x16_bf16 v[82:97], v[236:239], v[110:113], v[82:97]
	v_cvt_pk_bf16_f32 v217, v218, v219
	v_cvt_pk_bf16_f32 v218, v220, v221
	v_cvt_pk_bf16_f32 v219, v222, v223
	s_waitcnt lgkmcnt(10)
	v_mfma_f32_32x32x16_bf16 v[2:17], v[192:195], v[166:169], v[2:17]
	ds_read_b64_tr_b16 v[232:233], v145 offset:41472
	ds_read_b64_tr_b16 v[234:235], v145 offset:43520
	s_waitcnt lgkmcnt(10)
	v_mfma_f32_32x32x16_bf16 v[2:17], v[200:203], v[170:173], v[2:17]
	ds_read_b64_tr_b16 v[236:237], v145 offset:45568
	ds_read_b64_tr_b16 v[238:239], v145 offset:47616
	s_waitcnt lgkmcnt(10)
	v_mfma_f32_32x32x16_bf16 v[2:17], v[208:211], v[174:177], v[2:17]
	ds_read_b64_tr_b16 v[166:167], v145 offset:33792
	ds_read_b64_tr_b16 v[168:169], v145 offset:35840
	s_waitcnt lgkmcnt(10)
	v_mfma_f32_32x32x16_bf16 v[2:17], v[216:219], v[178:181], v[2:17]
	ds_read_b64_tr_b16 v[170:171], v145 offset:37888
	ds_read_b64_tr_b16 v[172:173], v145 offset:39936
	v_exp_f32_e32 v66, v66
	v_exp_f32_e32 v67, v67
	v_exp_f32_e32 v68, v68
	s_waitcnt lgkmcnt(10)
	v_mfma_f32_32x32x16_bf16 v[18:33], v[192:195], v[224:227], v[18:33]
	ds_read_b64_tr_b16 v[174:175], v145 offset:41984
	ds_read_b64_tr_b16 v[176:177], v145 offset:44032
	v_exp_f32_e32 v69, v69
	v_exp_f32_e32 v70, v70
	s_waitcnt lgkmcnt(10)
	v_mfma_f32_32x32x16_bf16 v[18:33], v[200:203], v[228:231], v[18:33]
	ds_read_b64_tr_b16 v[178:179], v145 offset:46080
	ds_read_b64_tr_b16 v[180:181], v145 offset:48128
	v_exp_f32_e32 v71, v71
	v_exp_f32_e32 v72, v72
	v_exp_f32_e32 v73, v73
	s_waitcnt lgkmcnt(10)
	v_mfma_f32_32x32x16_bf16 v[18:33], v[208:211], v[232:235], v[18:33]
	ds_read_b64_tr_b16 v[224:225], v145 offset:34304
	ds_read_b64_tr_b16 v[226:227], v145 offset:36352
	v_exp_f32_e32 v74, v74
	v_exp_f32_e32 v75, v75
	s_waitcnt lgkmcnt(10)
	v_mfma_f32_32x32x16_bf16 v[18:33], v[216:219], v[236:239], v[18:33]
	ds_read_b64_tr_b16 v[228:229], v145 offset:38400
	ds_read_b64_tr_b16 v[230:231], v145 offset:40448
	v_exp_f32_e32 v76, v76
	v_exp_f32_e32 v77, v77
	v_exp_f32_e32 v78, v78
	s_waitcnt lgkmcnt(10)
	v_mfma_f32_32x32x16_bf16 v[34:49], v[192:195], v[166:169], v[34:49]
	ds_read_b64_tr_b16 v[232:233], v145 offset:42496
	ds_read_b64_tr_b16 v[234:235], v145 offset:44544
	ds_read_b128 v[166:169], v240 offset:49152
	v_exp_f32_e32 v79, v79
	v_exp_f32_e32 v80, v80
	s_waitcnt lgkmcnt(11)
	v_mfma_f32_32x32x16_bf16 v[34:49], v[200:203], v[170:173], v[34:49]
	ds_read_b64_tr_b16 v[236:237], v145 offset:46592
	ds_read_b64_tr_b16 v[238:239], v145 offset:48640
	ds_read_b128 v[170:173], v240 offset:57344
	v_exp_f32_e32 v81, v81
	v_exp_f32_e32 v82, v82
	v_exp_f32_e32 v83, v83
	s_waitcnt lgkmcnt(12)
	v_mfma_f32_32x32x16_bf16 v[34:49], v[208:211], v[174:177], v[34:49]
	ds_read_b128 v[174:177], v241 offset:49152
	v_exp_f32_e32 v84, v84
	v_exp_f32_e32 v85, v85
	s_waitcnt lgkmcnt(11)
	v_mfma_f32_32x32x16_bf16 v[34:49], v[216:219], v[178:181], v[34:49]
	ds_read_b128 v[178:181], v241 offset:57344
	v_exp_f32_e32 v86, v86
	v_exp_f32_e32 v87, v87
	v_exp_f32_e32 v88, v88
	s_waitcnt lgkmcnt(10)
	v_mfma_f32_32x32x16_bf16 v[50:65], v[192:195], v[224:227], v[50:65]
	ds_read_b128 v[224:227], v242 offset:49152
	v_exp_f32_e32 v89, v89
	v_exp_f32_e32 v90, v90
	s_waitcnt lgkmcnt(9)
	v_mfma_f32_32x32x16_bf16 v[50:65], v[200:203], v[228:231], v[50:65]
	ds_read_b128 v[228:231], v242 offset:57344
	v_exp_f32_e32 v91, v91
	v_exp_f32_e32 v92, v92
	v_exp_f32_e32 v93, v93
	s_waitcnt lgkmcnt(8)
	v_mfma_f32_32x32x16_bf16 v[50:65], v[208:211], v[232:235], v[50:65]
	ds_read_b128 v[232:235], v243 offset:49152
	v_exp_f32_e32 v94, v94
	v_exp_f32_e32 v95, v95
	s_waitcnt lgkmcnt(6)
	v_mfma_f32_32x32x16_bf16 v[50:65], v[216:219], v[236:239], v[50:65]
	ds_read_b128 v[236:239], v243 offset:57344
	v_exp_f32_e32 v96, v96
	v_exp_f32_e32 v97, v97
	s_waitcnt vmcnt(0)
	s_barrier
	v_mfma_f32_32x32x16_bf16 v[192:207], v[166:169], v[106:109], 0
	s_add_i32 m0, s45, 0x8000
	v_add_f32_e32 v131, v66, v67
	v_add_f32_e32 v132, v68, v69
	v_add_f32_e32 v131, v70, v131
	global_load_lds_dwordx4 v148, s[64:65]
	s_waitcnt lgkmcnt(6)
	v_mfma_f32_32x32x16_bf16 v[208:223], v[170:173], v[106:109], 0
	s_add_i32 m0, s45, 0xc000
	v_add_f32_e32 v132, v71, v132
	v_add_f32_e32 v131, v72, v131
	v_add_f32_e32 v132, v73, v132
	global_load_lds_dwordx4 v146, s[62:63]
	ds_read_b128 v[166:169], v244 offset:49152
	ds_read_b128 v[170:173], v244 offset:57344
	s_waitcnt lgkmcnt(7)
	v_mfma_f32_32x32x16_bf16 v[192:207], v[174:177], v[102:105], v[192:207]
	s_add_i32 m0, s45, 0xa000
	v_add_f32_e32 v131, v74, v131
	v_add_f32_e32 v132, v75, v132
	v_add_f32_e32 v131, v76, v131
	global_load_lds_dwordx4 v152, s[64:65]
	s_waitcnt lgkmcnt(6)
	v_mfma_f32_32x32x16_bf16 v[208:223], v[178:181], v[102:105], v[208:223]
	s_add_i32 m0, s45, 0xe000
	v_add_f32_e32 v132, v77, v132
	v_add_f32_e32 v131, v78, v131
	v_add_f32_e32 v132, v79, v132
	global_load_lds_dwordx4 v150, s[62:63]
	s_add_u32 s62, s62, 0x4000
	s_addc_u32 s63, s63, 0
	s_add_u32 s64, s64, 0x4000
	s_addc_u32 s65, s65, 0
	ds_read_b128 v[174:177], v245 offset:49152
	ds_read_b128 v[178:181], v245 offset:57344
	s_waitcnt lgkmcnt(7)
	v_mfma_f32_32x32x16_bf16 v[192:207], v[224:227], v[98:101], v[192:207]
	v_add_f32_e32 v131, v80, v131
	v_add_f32_e32 v132, v81, v132
	v_add_f32_e32 v131, v82, v131
	s_waitcnt lgkmcnt(6)
	v_mfma_f32_32x32x16_bf16 v[208:223], v[228:231], v[98:101], v[208:223]
	v_add_f32_e32 v132, v83, v132
	v_add_f32_e32 v131, v84, v131
	v_add_f32_e32 v132, v85, v132
	ds_read_b128 v[224:227], v246 offset:49152
	ds_read_b128 v[228:231], v246 offset:57344
	s_waitcnt lgkmcnt(7)
	v_mfma_f32_32x32x16_bf16 v[192:207], v[232:235], v[126:129], v[192:207]
	v_add_f32_e32 v131, v86, v131
	v_add_f32_e32 v132, v87, v132
	v_add_f32_e32 v131, v88, v131
	s_waitcnt lgkmcnt(6)
	v_mfma_f32_32x32x16_bf16 v[208:223], v[236:239], v[126:129], v[208:223]
	v_add_f32_e32 v132, v89, v132
	v_add_f32_e32 v131, v90, v131
	v_add_f32_e32 v132, v91, v132
	ds_read_b128 v[232:235], v247 offset:49152
	ds_read_b128 v[236:239], v247 offset:57344
	s_waitcnt lgkmcnt(7)
	v_mfma_f32_32x32x16_bf16 v[192:207], v[166:169], v[122:125], v[192:207]
	v_add_f32_e32 v131, v92, v131
	v_add_f32_e32 v132, v93, v132
	v_add_f32_e32 v131, v94, v131
	s_waitcnt lgkmcnt(6)
	v_mfma_f32_32x32x16_bf16 v[208:223], v[170:173], v[122:125], v[208:223]
	v_add_f32_e32 v132, v95, v132
	v_add_f32_e32 v131, v96, v131
	v_add_f32_e32 v132, v97, v132
	ds_read_b64_tr_b16 v[166:167], v130 offset:0
	ds_read_b64_tr_b16 v[168:169], v130 offset:2048
	ds_read_b64_tr_b16 v[170:171], v130 offset:4096
	ds_read_b64_tr_b16 v[172:173], v130 offset:6144
	s_waitcnt lgkmcnt(9)
	v_mfma_f32_32x32x16_bf16 v[192:207], v[174:177], v[118:121], v[192:207]
	v_add_f32_e32 v131, v131, v132
	v_add_f32_e32 v165, v165, v131
	v_cvt_pk_bf16_f32 v66, v66, v67
	s_waitcnt lgkmcnt(8)
	v_mfma_f32_32x32x16_bf16 v[208:223], v[178:181], v[118:121], v[208:223]
	v_cvt_pk_bf16_f32 v67, v68, v69
	v_cvt_pk_bf16_f32 v68, v70, v71
	v_cvt_pk_bf16_f32 v69, v72, v73
	ds_read_b64_tr_b16 v[174:175], v130 offset:8192
	ds_read_b64_tr_b16 v[176:177], v130 offset:10240
	ds_read_b64_tr_b16 v[178:179], v130 offset:12288
	ds_read_b64_tr_b16 v[180:181], v130 offset:14336
	s_waitcnt lgkmcnt(11)
	v_mfma_f32_32x32x16_bf16 v[192:207], v[224:227], v[114:117], v[192:207]
	v_cvt_pk_bf16_f32 v74, v74, v75
	v_cvt_pk_bf16_f32 v75, v76, v77
	v_cvt_pk_bf16_f32 v76, v78, v79
	s_waitcnt lgkmcnt(10)
	v_mfma_f32_32x32x16_bf16 v[208:223], v[228:231], v[114:117], v[208:223]
	v_cvt_pk_bf16_f32 v77, v80, v81
	v_cvt_pk_bf16_f32 v82, v82, v83
	v_cvt_pk_bf16_f32 v83, v84, v85
	ds_read_b64_tr_b16 v[224:225], v130 offset:512
	ds_read_b64_tr_b16 v[226:227], v130 offset:2560
	ds_read_b64_tr_b16 v[228:229], v130 offset:4608
	ds_read_b64_tr_b16 v[230:231], v130 offset:6656
	s_waitcnt lgkmcnt(13)
	v_mfma_f32_32x32x16_bf16 v[192:207], v[232:235], v[110:113], v[192:207]
	v_cvt_pk_bf16_f32 v84, v86, v87
	v_cvt_pk_bf16_f32 v85, v88, v89
	v_cvt_pk_bf16_f32 v90, v90, v91
	s_waitcnt lgkmcnt(12)
	v_mfma_f32_32x32x16_bf16 v[208:223], v[236:239], v[110:113], v[208:223]
	v_cvt_pk_bf16_f32 v91, v92, v93
	v_cvt_pk_bf16_f32 v92, v94, v95
	v_cvt_pk_bf16_f32 v93, v96, v97
	s_waitcnt lgkmcnt(10)
	v_mfma_f32_32x32x16_bf16 v[2:17], v[66:69], v[166:169], v[2:17]
	ds_read_b64_tr_b16 v[232:233], v130 offset:8704
	ds_read_b64_tr_b16 v[234:235], v130 offset:10752
	s_waitcnt lgkmcnt(10)
	v_mfma_f32_32x32x16_bf16 v[2:17], v[74:77], v[170:173], v[2:17]
	ds_read_b64_tr_b16 v[236:237], v130 offset:12800
	ds_read_b64_tr_b16 v[238:239], v130 offset:14848
	s_waitcnt lgkmcnt(10)
	v_mfma_f32_32x32x16_bf16 v[2:17], v[82:85], v[174:177], v[2:17]
	ds_read_b64_tr_b16 v[166:167], v130 offset:1024
	ds_read_b64_tr_b16 v[168:169], v130 offset:3072
	s_waitcnt lgkmcnt(10)
	v_mfma_f32_32x32x16_bf16 v[2:17], v[90:93], v[178:181], v[2:17]
	ds_read_b64_tr_b16 v[170:171], v130 offset:5120
	ds_read_b64_tr_b16 v[172:173], v130 offset:7168
	v_exp_f32_e32 v192, v192
	v_exp_f32_e32 v193, v193
	v_exp_f32_e32 v194, v194
	s_waitcnt lgkmcnt(10)
	v_mfma_f32_32x32x16_bf16 v[18:33], v[66:69], v[224:227], v[18:33]
	ds_read_b64_tr_b16 v[174:175], v130 offset:9216
	ds_read_b64_tr_b16 v[176:177], v130 offset:11264
	v_exp_f32_e32 v195, v195
	v_exp_f32_e32 v196, v196
	s_waitcnt lgkmcnt(10)
	v_mfma_f32_32x32x16_bf16 v[18:33], v[74:77], v[228:231], v[18:33]
	ds_read_b64_tr_b16 v[178:179], v130 offset:13312
	ds_read_b64_tr_b16 v[180:181], v130 offset:15360
	v_exp_f32_e32 v197, v197
	v_exp_f32_e32 v198, v198
	v_exp_f32_e32 v199, v199
	s_waitcnt lgkmcnt(10)
	v_mfma_f32_32x32x16_bf16 v[18:33], v[82:85], v[232:235], v[18:33]
	ds_read_b64_tr_b16 v[224:225], v130 offset:1536
	ds_read_b64_tr_b16 v[226:227], v130 offset:3584
	v_exp_f32_e32 v200, v200
	v_exp_f32_e32 v201, v201
	s_waitcnt lgkmcnt(10)
	v_mfma_f32_32x32x16_bf16 v[18:33], v[90:93], v[236:239], v[18:33]
	ds_read_b64_tr_b16 v[228:229], v130 offset:5632
	ds_read_b64_tr_b16 v[230:231], v130 offset:7680
	v_exp_f32_e32 v202, v202
	v_exp_f32_e32 v203, v203
	v_exp_f32_e32 v204, v204
	s_waitcnt lgkmcnt(10)
	v_mfma_f32_32x32x16_bf16 v[34:49], v[66:69], v[166:169], v[34:49]
	ds_read_b64_tr_b16 v[232:233], v130 offset:9728
	ds_read_b64_tr_b16 v[234:235], v130 offset:11776
	ds_read_b128 v[166:169], v183 offset:16384
	v_exp_f32_e32 v205, v205
	v_exp_f32_e32 v206, v206
	s_waitcnt lgkmcnt(11)
	v_mfma_f32_32x32x16_bf16 v[34:49], v[74:77], v[170:173], v[34:49]
	ds_read_b64_tr_b16 v[236:237], v130 offset:13824
	ds_read_b64_tr_b16 v[238:239], v130 offset:15872
	ds_read_b128 v[170:173], v183 offset:24576
	v_exp_f32_e32 v207, v207
	v_exp_f32_e32 v208, v208
	v_exp_f32_e32 v209, v209
	s_waitcnt lgkmcnt(12)
	v_mfma_f32_32x32x16_bf16 v[34:49], v[82:85], v[174:177], v[34:49]
	ds_read_b128 v[174:177], v184 offset:16384
	v_exp_f32_e32 v210, v210
	v_exp_f32_e32 v211, v211
	s_waitcnt lgkmcnt(11)
	v_mfma_f32_32x32x16_bf16 v[34:49], v[90:93], v[178:181], v[34:49]
	ds_read_b128 v[178:181], v184 offset:24576
	v_exp_f32_e32 v212, v212
	v_exp_f32_e32 v213, v213
	v_exp_f32_e32 v214, v214
	s_waitcnt lgkmcnt(10)
	v_mfma_f32_32x32x16_bf16 v[50:65], v[66:69], v[224:227], v[50:65]
	ds_read_b128 v[224:227], v185 offset:16384
	v_exp_f32_e32 v215, v215
	v_exp_f32_e32 v216, v216
	s_waitcnt lgkmcnt(9)
	v_mfma_f32_32x32x16_bf16 v[50:65], v[74:77], v[228:231], v[50:65]
	ds_read_b128 v[228:231], v185 offset:24576
	v_exp_f32_e32 v217, v217
	v_exp_f32_e32 v218, v218
	v_exp_f32_e32 v219, v219
	s_waitcnt lgkmcnt(8)
	v_mfma_f32_32x32x16_bf16 v[50:65], v[82:85], v[232:235], v[50:65]
	ds_read_b128 v[232:235], v186 offset:16384
	v_exp_f32_e32 v220, v220
	v_exp_f32_e32 v221, v221
	s_waitcnt lgkmcnt(6)
	v_mfma_f32_32x32x16_bf16 v[50:65], v[90:93], v[236:239], v[50:65]
	ds_read_b128 v[236:239], v186 offset:24576
	v_exp_f32_e32 v222, v222
	v_exp_f32_e32 v223, v223
	s_waitcnt vmcnt(0)
	s_barrier
	v_mfma_f32_32x32x16_bf16 v[66:81], v[166:169], v[106:109], 0
	s_add_i32 m0, s45, 0x10000
	v_add_f32_e32 v131, v192, v193
	v_add_f32_e32 v132, v194, v195
	v_add_f32_e32 v131, v196, v131
	global_load_lds_dwordx4 v148, s[64:65]
	s_waitcnt lgkmcnt(6)
	v_mfma_f32_32x32x16_bf16 v[82:97], v[170:173], v[106:109], 0
	s_add_i32 m0, s45, 0x14000
	v_add_f32_e32 v132, v197, v132
	v_add_f32_e32 v131, v198, v131
	v_add_f32_e32 v132, v199, v132
	global_load_lds_dwordx4 v146, s[62:63]
	ds_read_b128 v[166:169], v187 offset:16384
	ds_read_b128 v[170:173], v187 offset:24576
	s_waitcnt lgkmcnt(7)
	v_mfma_f32_32x32x16_bf16 v[66:81], v[174:177], v[102:105], v[66:81]
	s_add_i32 m0, s45, 0x12000
	v_add_f32_e32 v131, v200, v131
	v_add_f32_e32 v132, v201, v132
	v_add_f32_e32 v131, v202, v131
	global_load_lds_dwordx4 v152, s[64:65]
	s_waitcnt lgkmcnt(6)
	v_mfma_f32_32x32x16_bf16 v[82:97], v[178:181], v[102:105], v[82:97]
	s_add_i32 m0, s45, 0x16000
	v_add_f32_e32 v132, v203, v132
	v_add_f32_e32 v131, v204, v131
	v_add_f32_e32 v132, v205, v132
	global_load_lds_dwordx4 v150, s[62:63]
	s_add_u32 s62, s62, 0x4000
	s_addc_u32 s63, s63, 0
	s_add_u32 s64, s64, 0x4000
	s_addc_u32 s65, s65, 0
	ds_read_b128 v[174:177], v188 offset:16384
	ds_read_b128 v[178:181], v188 offset:24576
	s_waitcnt lgkmcnt(7)
	v_mfma_f32_32x32x16_bf16 v[66:81], v[224:227], v[98:101], v[66:81]
	v_add_f32_e32 v131, v206, v131
	v_add_f32_e32 v132, v207, v132
	v_add_f32_e32 v131, v208, v131
	s_waitcnt lgkmcnt(6)
	v_mfma_f32_32x32x16_bf16 v[82:97], v[228:231], v[98:101], v[82:97]
	v_add_f32_e32 v132, v209, v132
	v_add_f32_e32 v131, v210, v131
	v_add_f32_e32 v132, v211, v132
	ds_read_b128 v[224:227], v189 offset:16384
	ds_read_b128 v[228:231], v189 offset:24576
	s_waitcnt lgkmcnt(7)
	v_mfma_f32_32x32x16_bf16 v[66:81], v[232:235], v[126:129], v[66:81]
	v_add_f32_e32 v131, v212, v131
	v_add_f32_e32 v132, v213, v132
	v_add_f32_e32 v131, v214, v131
	s_waitcnt lgkmcnt(6)
	v_mfma_f32_32x32x16_bf16 v[82:97], v[236:239], v[126:129], v[82:97]
	v_add_f32_e32 v132, v215, v132
	v_add_f32_e32 v131, v216, v131
	v_add_f32_e32 v132, v217, v132
	ds_read_b128 v[232:235], v190 offset:16384
	ds_read_b128 v[236:239], v190 offset:24576
	s_waitcnt lgkmcnt(7)
	v_mfma_f32_32x32x16_bf16 v[66:81], v[166:169], v[122:125], v[66:81]
	v_add_f32_e32 v131, v218, v131
	v_add_f32_e32 v132, v219, v132
	v_add_f32_e32 v131, v220, v131
	s_waitcnt lgkmcnt(6)
	v_mfma_f32_32x32x16_bf16 v[82:97], v[170:173], v[122:125], v[82:97]
	v_add_f32_e32 v132, v221, v132
	v_add_f32_e32 v131, v222, v131
	v_add_f32_e32 v132, v223, v132
	ds_read_b64_tr_b16 v[166:167], v130 offset:32768
	ds_read_b64_tr_b16 v[168:169], v130 offset:34816
	ds_read_b64_tr_b16 v[170:171], v130 offset:36864
	ds_read_b64_tr_b16 v[172:173], v130 offset:38912
	s_waitcnt lgkmcnt(9)
	v_mfma_f32_32x32x16_bf16 v[66:81], v[174:177], v[118:121], v[66:81]
	v_add_f32_e32 v131, v131, v132
	v_add_f32_e32 v165, v165, v131
	v_cvt_pk_bf16_f32 v192, v192, v193
	s_waitcnt lgkmcnt(8)
	v_mfma_f32_32x32x16_bf16 v[82:97], v[178:181], v[118:121], v[82:97]
	v_cvt_pk_bf16_f32 v193, v194, v195
	v_cvt_pk_bf16_f32 v194, v196, v197
	v_cvt_pk_bf16_f32 v195, v198, v199
	ds_read_b64_tr_b16 v[174:175], v130 offset:40960
	ds_read_b64_tr_b16 v[176:177], v130 offset:43008
	ds_read_b64_tr_b16 v[178:179], v130 offset:45056
	ds_read_b64_tr_b16 v[180:181], v130 offset:47104
	s_waitcnt lgkmcnt(11)
	v_mfma_f32_32x32x16_bf16 v[66:81], v[224:227], v[114:117], v[66:81]
	v_cvt_pk_bf16_f32 v200, v200, v201
	v_cvt_pk_bf16_f32 v201, v202, v203
	v_cvt_pk_bf16_f32 v202, v204, v205
	s_waitcnt lgkmcnt(10)
	v_mfma_f32_32x32x16_bf16 v[82:97], v[228:231], v[114:117], v[82:97]
	v_cvt_pk_bf16_f32 v203, v206, v207
	v_cvt_pk_bf16_f32 v208, v208, v209
	v_cvt_pk_bf16_f32 v209, v210, v211
	ds_read_b64_tr_b16 v[224:225], v130 offset:33280
	ds_read_b64_tr_b16 v[226:227], v130 offset:35328
	ds_read_b64_tr_b16 v[228:229], v130 offset:37376
	ds_read_b64_tr_b16 v[230:231], v130 offset:39424
	s_waitcnt lgkmcnt(13)
	v_mfma_f32_32x32x16_bf16 v[66:81], v[232:235], v[110:113], v[66:81]
	v_cvt_pk_bf16_f32 v210, v212, v213
	v_cvt_pk_bf16_f32 v211, v214, v215
	v_cvt_pk_bf16_f32 v216, v216, v217
	s_waitcnt lgkmcnt(12)
	v_mfma_f32_32x32x16_bf16 v[82:97], v[236:239], v[110:113], v[82:97]
	v_cvt_pk_bf16_f32 v217, v218, v219
	v_cvt_pk_bf16_f32 v218, v220, v221
	v_cvt_pk_bf16_f32 v219, v222, v223
	s_waitcnt lgkmcnt(10)
	v_mfma_f32_32x32x16_bf16 v[2:17], v[192:195], v[166:169], v[2:17]
	ds_read_b64_tr_b16 v[232:233], v130 offset:41472
	ds_read_b64_tr_b16 v[234:235], v130 offset:43520
	s_waitcnt lgkmcnt(10)
	v_mfma_f32_32x32x16_bf16 v[2:17], v[200:203], v[170:173], v[2:17]
	ds_read_b64_tr_b16 v[236:237], v130 offset:45568
	ds_read_b64_tr_b16 v[238:239], v130 offset:47616
	s_waitcnt lgkmcnt(10)
	v_mfma_f32_32x32x16_bf16 v[2:17], v[208:211], v[174:177], v[2:17]
	ds_read_b64_tr_b16 v[166:167], v130 offset:33792
	ds_read_b64_tr_b16 v[168:169], v130 offset:35840
	s_waitcnt lgkmcnt(10)
	v_mfma_f32_32x32x16_bf16 v[2:17], v[216:219], v[178:181], v[2:17]
	ds_read_b64_tr_b16 v[170:171], v130 offset:37888
	ds_read_b64_tr_b16 v[172:173], v130 offset:39936
	v_exp_f32_e32 v66, v66
	v_exp_f32_e32 v67, v67
	v_exp_f32_e32 v68, v68
	s_waitcnt lgkmcnt(10)
	v_mfma_f32_32x32x16_bf16 v[18:33], v[192:195], v[224:227], v[18:33]
	ds_read_b64_tr_b16 v[174:175], v130 offset:41984
	ds_read_b64_tr_b16 v[176:177], v130 offset:44032
	v_exp_f32_e32 v69, v69
	v_exp_f32_e32 v70, v70
	s_waitcnt lgkmcnt(10)
	v_mfma_f32_32x32x16_bf16 v[18:33], v[200:203], v[228:231], v[18:33]
	ds_read_b64_tr_b16 v[178:179], v130 offset:46080
	ds_read_b64_tr_b16 v[180:181], v130 offset:48128
	v_exp_f32_e32 v71, v71
	v_exp_f32_e32 v72, v72
	v_exp_f32_e32 v73, v73
	s_waitcnt lgkmcnt(10)
	v_mfma_f32_32x32x16_bf16 v[18:33], v[208:211], v[232:235], v[18:33]
	ds_read_b64_tr_b16 v[224:225], v130 offset:34304
	ds_read_b64_tr_b16 v[226:227], v130 offset:36352
	v_exp_f32_e32 v74, v74
	v_exp_f32_e32 v75, v75
	s_waitcnt lgkmcnt(10)
	v_mfma_f32_32x32x16_bf16 v[18:33], v[216:219], v[236:239], v[18:33]
	ds_read_b64_tr_b16 v[228:229], v130 offset:38400
	ds_read_b64_tr_b16 v[230:231], v130 offset:40448
	v_exp_f32_e32 v76, v76
	v_exp_f32_e32 v77, v77
	v_exp_f32_e32 v78, v78
	s_waitcnt lgkmcnt(10)
	v_mfma_f32_32x32x16_bf16 v[34:49], v[192:195], v[166:169], v[34:49]
	ds_read_b64_tr_b16 v[232:233], v130 offset:42496
	ds_read_b64_tr_b16 v[234:235], v130 offset:44544
	ds_read_b128 v[166:169], v183 offset:49152
	v_exp_f32_e32 v79, v79
	v_exp_f32_e32 v80, v80
	s_waitcnt lgkmcnt(11)
	v_mfma_f32_32x32x16_bf16 v[34:49], v[200:203], v[170:173], v[34:49]
	ds_read_b64_tr_b16 v[236:237], v130 offset:46592
	ds_read_b64_tr_b16 v[238:239], v130 offset:48640
	ds_read_b128 v[170:173], v183 offset:57344
	v_exp_f32_e32 v81, v81
	v_exp_f32_e32 v82, v82
	v_exp_f32_e32 v83, v83
	s_waitcnt lgkmcnt(12)
	v_mfma_f32_32x32x16_bf16 v[34:49], v[208:211], v[174:177], v[34:49]
	ds_read_b128 v[174:177], v184 offset:49152
	v_exp_f32_e32 v84, v84
	v_exp_f32_e32 v85, v85
	s_waitcnt lgkmcnt(11)
	v_mfma_f32_32x32x16_bf16 v[34:49], v[216:219], v[178:181], v[34:49]
	ds_read_b128 v[178:181], v184 offset:57344
	v_exp_f32_e32 v86, v86
	v_exp_f32_e32 v87, v87
	v_exp_f32_e32 v88, v88
	s_waitcnt lgkmcnt(10)
	v_mfma_f32_32x32x16_bf16 v[50:65], v[192:195], v[224:227], v[50:65]
	ds_read_b128 v[224:227], v185 offset:49152
	v_exp_f32_e32 v89, v89
	v_exp_f32_e32 v90, v90
	s_waitcnt lgkmcnt(9)
	v_mfma_f32_32x32x16_bf16 v[50:65], v[200:203], v[228:231], v[50:65]
	ds_read_b128 v[228:231], v185 offset:57344
	v_exp_f32_e32 v91, v91
	v_exp_f32_e32 v92, v92
	v_exp_f32_e32 v93, v93
	s_waitcnt lgkmcnt(8)
	v_mfma_f32_32x32x16_bf16 v[50:65], v[208:211], v[232:235], v[50:65]
	ds_read_b128 v[232:235], v186 offset:49152
	v_exp_f32_e32 v94, v94
	v_exp_f32_e32 v95, v95
	s_waitcnt lgkmcnt(6)
	v_mfma_f32_32x32x16_bf16 v[50:65], v[216:219], v[236:239], v[50:65]
	ds_read_b128 v[236:239], v186 offset:57344
	v_exp_f32_e32 v96, v96
	v_exp_f32_e32 v97, v97
	s_waitcnt vmcnt(0)
	s_barrier
	s_sub_u32 s66, s66, 1
	s_cmp_lg_u32 s66, 0
	s_cbranch_scc1 .Lattn_loop
	v_mfma_f32_32x32x16_bf16 v[192:207], v[166:169], v[106:109], 0
	s_add_i32 m0, s45, 0x18000
	v_add_f32_e32 v131, v66, v67
	v_add_f32_e32 v132, v68, v69
	v_add_f32_e32 v131, v70, v131
	global_load_lds_dwordx4 v148, s[64:65]
	s_waitcnt lgkmcnt(6)
	v_mfma_f32_32x32x16_bf16 v[208:223], v[170:173], v[106:109], 0
	s_add_i32 m0, s45, 0x1c000
	v_add_f32_e32 v132, v71, v132
	v_add_f32_e32 v131, v72, v131
	v_add_f32_e32 v132, v73, v132
	global_load_lds_dwordx4 v146, s[62:63]
	ds_read_b128 v[166:169], v187 offset:49152
	ds_read_b128 v[170:173], v187 offset:57344
	s_waitcnt lgkmcnt(7)
	v_mfma_f32_32x32x16_bf16 v[192:207], v[174:177], v[102:105], v[192:207]
	s_add_i32 m0, s45, 0x1a000
	v_add_f32_e32 v131, v74, v131
	v_add_f32_e32 v132, v75, v132
	v_add_f32_e32 v131, v76, v131
	global_load_lds_dwordx4 v152, s[64:65]
	s_waitcnt lgkmcnt(6)
	v_mfma_f32_32x32x16_bf16 v[208:223], v[178:181], v[102:105], v[208:223]
	s_add_i32 m0, s45, 0x1e000
	v_add_f32_e32 v132, v77, v132
	v_add_f32_e32 v131, v78, v131
	v_add_f32_e32 v132, v79, v132
	global_load_lds_dwordx4 v150, s[62:63]
	s_add_u32 s62, s62, 0x4000
	s_addc_u32 s63, s63, 0
	s_add_u32 s64, s64, 0x4000
	s_addc_u32 s65, s65, 0
	ds_read_b128 v[174:177], v188 offset:49152
	ds_read_b128 v[178:181], v188 offset:57344
	s_waitcnt lgkmcnt(7)
	v_mfma_f32_32x32x16_bf16 v[192:207], v[224:227], v[98:101], v[192:207]
	v_add_f32_e32 v131, v80, v131
	v_add_f32_e32 v132, v81, v132
	v_add_f32_e32 v131, v82, v131
	s_waitcnt lgkmcnt(6)
	v_mfma_f32_32x32x16_bf16 v[208:223], v[228:231], v[98:101], v[208:223]
	v_add_f32_e32 v132, v83, v132
	v_add_f32_e32 v131, v84, v131
	v_add_f32_e32 v132, v85, v132
	ds_read_b128 v[224:227], v189 offset:49152
	ds_read_b128 v[228:231], v189 offset:57344
	s_waitcnt lgkmcnt(7)
	v_mfma_f32_32x32x16_bf16 v[192:207], v[232:235], v[126:129], v[192:207]
	v_add_f32_e32 v131, v86, v131
	v_add_f32_e32 v132, v87, v132
	v_add_f32_e32 v131, v88, v131
	s_waitcnt lgkmcnt(6)
	v_mfma_f32_32x32x16_bf16 v[208:223], v[236:239], v[126:129], v[208:223]
	v_add_f32_e32 v132, v89, v132
	v_add_f32_e32 v131, v90, v131
	v_add_f32_e32 v132, v91, v132
	ds_read_b128 v[232:235], v190 offset:49152
	ds_read_b128 v[236:239], v190 offset:57344
	s_waitcnt lgkmcnt(7)
	v_mfma_f32_32x32x16_bf16 v[192:207], v[166:169], v[122:125], v[192:207]
	v_add_f32_e32 v131, v92, v131
	v_add_f32_e32 v132, v93, v132
	v_add_f32_e32 v131, v94, v131
	s_waitcnt lgkmcnt(6)
	v_mfma_f32_32x32x16_bf16 v[208:223], v[170:173], v[122:125], v[208:223]
	v_add_f32_e32 v132, v95, v132
	v_add_f32_e32 v131, v96, v131
	v_add_f32_e32 v132, v97, v132
	ds_read_b64_tr_b16 v[166:167], v145 offset:0
	ds_read_b64_tr_b16 v[168:169], v145 offset:2048
	ds_read_b64_tr_b16 v[170:171], v145 offset:4096
	ds_read_b64_tr_b16 v[172:173], v145 offset:6144
	s_waitcnt lgkmcnt(9)
	v_mfma_f32_32x32x16_bf16 v[192:207], v[174:177], v[118:121], v[192:207]
	v_add_f32_e32 v131, v131, v132
	v_add_f32_e32 v165, v165, v131
	v_cvt_pk_bf16_f32 v66, v66, v67
	s_waitcnt lgkmcnt(8)
	v_mfma_f32_32x32x16_bf16 v[208:223], v[178:181], v[118:121], v[208:223]
	v_cvt_pk_bf16_f32 v67, v68, v69
	v_cvt_pk_bf16_f32 v68, v70, v71
	v_cvt_pk_bf16_f32 v69, v72, v73
	ds_read_b64_tr_b16 v[174:175], v145 offset:8192
	ds_read_b64_tr_b16 v[176:177], v145 offset:10240
	ds_read_b64_tr_b16 v[178:179], v145 offset:12288
	ds_read_b64_tr_b16 v[180:181], v145 offset:14336
	s_waitcnt lgkmcnt(11)
	v_mfma_f32_32x32x16_bf16 v[192:207], v[224:227], v[114:117], v[192:207]
	v_cvt_pk_bf16_f32 v74, v74, v75
	v_cvt_pk_bf16_f32 v75, v76, v77
	v_cvt_pk_bf16_f32 v76, v78, v79
	s_waitcnt lgkmcnt(10)
	v_mfma_f32_32x32x16_bf16 v[208:223], v[228:231], v[114:117], v[208:223]
	v_cvt_pk_bf16_f32 v77, v80, v81
	v_cvt_pk_bf16_f32 v82, v82, v83
	v_cvt_pk_bf16_f32 v83, v84, v85
	ds_read_b64_tr_b16 v[224:225], v145 offset:512
	ds_read_b64_tr_b16 v[226:227], v145 offset:2560
	ds_read_b64_tr_b16 v[228:229], v145 offset:4608
	ds_read_b64_tr_b16 v[230:231], v145 offset:6656
	s_waitcnt lgkmcnt(13)
	v_mfma_f32_32x32x16_bf16 v[192:207], v[232:235], v[110:113], v[192:207]
	v_cvt_pk_bf16_f32 v84, v86, v87
	v_cvt_pk_bf16_f32 v85, v88, v89
	v_cvt_pk_bf16_f32 v90, v90, v91
	s_waitcnt lgkmcnt(12)
	v_mfma_f32_32x32x16_bf16 v[208:223], v[236:239], v[110:113], v[208:223]
	v_cvt_pk_bf16_f32 v91, v92, v93
	v_cvt_pk_bf16_f32 v92, v94, v95
	v_cvt_pk_bf16_f32 v93, v96, v97
	s_waitcnt lgkmcnt(10)
	v_mfma_f32_32x32x16_bf16 v[2:17], v[66:69], v[166:169], v[2:17]
	ds_read_b64_tr_b16 v[232:233], v145 offset:8704
	ds_read_b64_tr_b16 v[234:235], v145 offset:10752
	s_waitcnt lgkmcnt(10)
	v_mfma_f32_32x32x16_bf16 v[2:17], v[74:77], v[170:173], v[2:17]
	ds_read_b64_tr_b16 v[236:237], v145 offset:12800
	ds_read_b64_tr_b16 v[238:239], v145 offset:14848
	s_waitcnt lgkmcnt(10)
	v_mfma_f32_32x32x16_bf16 v[2:17], v[82:85], v[174:177], v[2:17]
	ds_read_b64_tr_b16 v[166:167], v145 offset:1024
	ds_read_b64_tr_b16 v[168:169], v145 offset:3072
	s_waitcnt lgkmcnt(10)
	v_mfma_f32_32x32x16_bf16 v[2:17], v[90:93], v[178:181], v[2:17]
	ds_read_b64_tr_b16 v[170:171], v145 offset:5120
	ds_read_b64_tr_b16 v[172:173], v145 offset:7168
	v_exp_f32_e32 v192, v192
	v_exp_f32_e32 v193, v193
	v_exp_f32_e32 v194, v194
	s_waitcnt lgkmcnt(10)
	v_mfma_f32_32x32x16_bf16 v[18:33], v[66:69], v[224:227], v[18:33]
	ds_read_b64_tr_b16 v[174:175], v145 offset:9216
	ds_read_b64_tr_b16 v[176:177], v145 offset:11264
	v_exp_f32_e32 v195, v195
	v_exp_f32_e32 v196, v196
	s_waitcnt lgkmcnt(10)
	v_mfma_f32_32x32x16_bf16 v[18:33], v[74:77], v[228:231], v[18:33]
	ds_read_b64_tr_b16 v[178:179], v145 offset:13312
	ds_read_b64_tr_b16 v[180:181], v145 offset:15360
	v_exp_f32_e32 v197, v197
	v_exp_f32_e32 v198, v198
	v_exp_f32_e32 v199, v199
	s_waitcnt lgkmcnt(10)
	v_mfma_f32_32x32x16_bf16 v[18:33], v[82:85], v[232:235], v[18:33]
	ds_read_b64_tr_b16 v[224:225], v145 offset:1536
	ds_read_b64_tr_b16 v[226:227], v145 offset:3584
	v_exp_f32_e32 v200, v200
	v_exp_f32_e32 v201, v201
	s_waitcnt lgkmcnt(10)
	v_mfma_f32_32x32x16_bf16 v[18:33], v[90:93], v[236:239], v[18:33]
	ds_read_b64_tr_b16 v[228:229], v145 offset:5632
	ds_read_b64_tr_b16 v[230:231], v145 offset:7680
	v_exp_f32_e32 v202, v202
	v_exp_f32_e32 v203, v203
	v_exp_f32_e32 v204, v204
	s_waitcnt lgkmcnt(10)
	v_mfma_f32_32x32x16_bf16 v[34:49], v[66:69], v[166:169], v[34:49]
	ds_read_b64_tr_b16 v[232:233], v145 offset:9728
	ds_read_b64_tr_b16 v[234:235], v145 offset:11776
	ds_read_b128 v[166:169], v240 offset:16384
	v_exp_f32_e32 v205, v205
	v_exp_f32_e32 v206, v206
	s_waitcnt lgkmcnt(11)
	v_mfma_f32_32x32x16_bf16 v[34:49], v[74:77], v[170:173], v[34:49]
	ds_read_b64_tr_b16 v[236:237], v145 offset:13824
	ds_read_b64_tr_b16 v[238:239], v145 offset:15872
	ds_read_b128 v[170:173], v240 offset:24576
	v_exp_f32_e32 v207, v207
	v_exp_f32_e32 v208, v208
	v_exp_f32_e32 v209, v209
	s_waitcnt lgkmcnt(12)
	v_mfma_f32_32x32x16_bf16 v[34:49], v[82:85], v[174:177], v[34:49]
	ds_read_b128 v[174:177], v241 offset:16384
	v_exp_f32_e32 v210, v210
	v_exp_f32_e32 v211, v211
	s_waitcnt lgkmcnt(11)
	v_mfma_f32_32x32x16_bf16 v[34:49], v[90:93], v[178:181], v[34:49]
	ds_read_b128 v[178:181], v241 offset:24576
	v_exp_f32_e32 v212, v212
	v_exp_f32_e32 v213, v213
	v_exp_f32_e32 v214, v214
	s_waitcnt lgkmcnt(10)
	v_mfma_f32_32x32x16_bf16 v[50:65], v[66:69], v[224:227], v[50:65]
	ds_read_b128 v[224:227], v242 offset:16384
	v_exp_f32_e32 v215, v215
	v_exp_f32_e32 v216, v216
	s_waitcnt lgkmcnt(9)
	v_mfma_f32_32x32x16_bf16 v[50:65], v[74:77], v[228:231], v[50:65]
	ds_read_b128 v[228:231], v242 offset:24576
	v_exp_f32_e32 v217, v217
	v_exp_f32_e32 v218, v218
	v_exp_f32_e32 v219, v219
	s_waitcnt lgkmcnt(8)
	v_mfma_f32_32x32x16_bf16 v[50:65], v[82:85], v[232:235], v[50:65]
	ds_read_b128 v[232:235], v243 offset:16384
	v_exp_f32_e32 v220, v220
	v_exp_f32_e32 v221, v221
	s_waitcnt lgkmcnt(6)
	v_mfma_f32_32x32x16_bf16 v[50:65], v[90:93], v[236:239], v[50:65]
	ds_read_b128 v[236:239], v243 offset:24576
	v_exp_f32_e32 v222, v222
	v_exp_f32_e32 v223, v223
	s_waitcnt vmcnt(0)
	s_barrier
	v_mfma_f32_32x32x16_bf16 v[66:81], v[166:169], v[106:109], 0
	v_add_f32_e32 v131, v192, v193
	v_add_f32_e32 v132, v194, v195
	v_add_f32_e32 v131, v196, v131
	s_waitcnt lgkmcnt(6)
	v_mfma_f32_32x32x16_bf16 v[82:97], v[170:173], v[106:109], 0
	v_add_f32_e32 v132, v197, v132
	v_add_f32_e32 v131, v198, v131
	v_add_f32_e32 v132, v199, v132
	ds_read_b128 v[166:169], v244 offset:16384
	ds_read_b128 v[170:173], v244 offset:24576
	s_waitcnt lgkmcnt(7)
	v_mfma_f32_32x32x16_bf16 v[66:81], v[174:177], v[102:105], v[66:81]
	v_add_f32_e32 v131, v200, v131
	v_add_f32_e32 v132, v201, v132
	v_add_f32_e32 v131, v202, v131
	s_waitcnt lgkmcnt(6)
	v_mfma_f32_32x32x16_bf16 v[82:97], v[178:181], v[102:105], v[82:97]
	v_add_f32_e32 v132, v203, v132
	v_add_f32_e32 v131, v204, v131
	v_add_f32_e32 v132, v205, v132
	ds_read_b128 v[174:177], v245 offset:16384
	ds_read_b128 v[178:181], v245 offset:24576
	s_waitcnt lgkmcnt(7)
	v_mfma_f32_32x32x16_bf16 v[66:81], v[224:227], v[98:101], v[66:81]
	v_add_f32_e32 v131, v206, v131
	v_add_f32_e32 v132, v207, v132
	v_add_f32_e32 v131, v208, v131
	s_waitcnt lgkmcnt(6)
	v_mfma_f32_32x32x16_bf16 v[82:97], v[228:231], v[98:101], v[82:97]
	v_add_f32_e32 v132, v209, v132
	v_add_f32_e32 v131, v210, v131
	v_add_f32_e32 v132, v211, v132
	ds_read_b128 v[224:227], v246 offset:16384
	ds_read_b128 v[228:231], v246 offset:24576
	s_waitcnt lgkmcnt(7)
	v_mfma_f32_32x32x16_bf16 v[66:81], v[232:235], v[126:129], v[66:81]
	v_add_f32_e32 v131, v212, v131
	v_add_f32_e32 v132, v213, v132
	v_add_f32_e32 v131, v214, v131
	s_waitcnt lgkmcnt(6)
	v_mfma_f32_32x32x16_bf16 v[82:97], v[236:239], v[126:129], v[82:97]
	v_add_f32_e32 v132, v215, v132
	v_add_f32_e32 v131, v216, v131
	v_add_f32_e32 v132, v217, v132
	ds_read_b128 v[232:235], v247 offset:16384
	ds_read_b128 v[236:239], v247 offset:24576
	s_waitcnt lgkmcnt(7)
	v_mfma_f32_32x32x16_bf16 v[66:81], v[166:169], v[122:125], v[66:81]
	v_add_f32_e32 v131, v218, v131
	v_add_f32_e32 v132, v219, v132
	v_add_f32_e32 v131, v220, v131
	s_waitcnt lgkmcnt(6)
	v_mfma_f32_32x32x16_bf16 v[82:97], v[170:173], v[122:125], v[82:97]
	v_add_f32_e32 v132, v221, v132
	v_add_f32_e32 v131, v222, v131
	v_add_f32_e32 v132, v223, v132
	ds_read_b64_tr_b16 v[166:167], v145 offset:32768
	ds_read_b64_tr_b16 v[168:169], v145 offset:34816
	ds_read_b64_tr_b16 v[170:171], v145 offset:36864
	ds_read_b64_tr_b16 v[172:173], v145 offset:38912
	s_waitcnt lgkmcnt(9)
	v_mfma_f32_32x32x16_bf16 v[66:81], v[174:177], v[118:121], v[66:81]
	v_add_f32_e32 v131, v131, v132
	v_add_f32_e32 v165, v165, v131
	v_cvt_pk_bf16_f32 v192, v192, v193
	s_waitcnt lgkmcnt(8)
	v_mfma_f32_32x32x16_bf16 v[82:97], v[178:181], v[118:121], v[82:97]
	v_cvt_pk_bf16_f32 v193, v194, v195
	v_cvt_pk_bf16_f32 v194, v196, v197
	v_cvt_pk_bf16_f32 v195, v198, v199
	ds_read_b64_tr_b16 v[174:175], v145 offset:40960
	ds_read_b64_tr_b16 v[176:177], v145 offset:43008
	ds_read_b64_tr_b16 v[178:179], v145 offset:45056
	ds_read_b64_tr_b16 v[180:181], v145 offset:47104
	s_waitcnt lgkmcnt(11)
	v_mfma_f32_32x32x16_bf16 v[66:81], v[224:227], v[114:117], v[66:81]
	v_cvt_pk_bf16_f32 v200, v200, v201
	v_cvt_pk_bf16_f32 v201, v202, v203
	v_cvt_pk_bf16_f32 v202, v204, v205
	s_waitcnt lgkmcnt(10)
	v_mfma_f32_32x32x16_bf16 v[82:97], v[228:231], v[114:117], v[82:97]
	v_cvt_pk_bf16_f32 v203, v206, v207
	v_cvt_pk_bf16_f32 v208, v208, v209
	v_cvt_pk_bf16_f32 v209, v210, v211
	ds_read_b64_tr_b16 v[224:225], v145 offset:33280
	ds_read_b64_tr_b16 v[226:227], v145 offset:35328
	ds_read_b64_tr_b16 v[228:229], v145 offset:37376
	ds_read_b64_tr_b16 v[230:231], v145 offset:39424
	s_waitcnt lgkmcnt(13)
	v_mfma_f32_32x32x16_bf16 v[66:81], v[232:235], v[110:113], v[66:81]
	v_cvt_pk_bf16_f32 v210, v212, v213
	v_cvt_pk_bf16_f32 v211, v214, v215
	v_cvt_pk_bf16_f32 v216, v216, v217
	s_waitcnt lgkmcnt(12)
	v_mfma_f32_32x32x16_bf16 v[82:97], v[236:239], v[110:113], v[82:97]
	v_cvt_pk_bf16_f32 v217, v218, v219
	v_cvt_pk_bf16_f32 v218, v220, v221
	v_cvt_pk_bf16_f32 v219, v222, v223
	s_waitcnt lgkmcnt(10)
	v_mfma_f32_32x32x16_bf16 v[2:17], v[192:195], v[166:169], v[2:17]
	ds_read_b64_tr_b16 v[232:233], v145 offset:41472
	ds_read_b64_tr_b16 v[234:235], v145 offset:43520
	s_waitcnt lgkmcnt(10)
	v_mfma_f32_32x32x16_bf16 v[2:17], v[200:203], v[170:173], v[2:17]
	ds_read_b64_tr_b16 v[236:237], v145 offset:45568
	ds_read_b64_tr_b16 v[238:239], v145 offset:47616
	s_waitcnt lgkmcnt(10)
	v_mfma_f32_32x32x16_bf16 v[2:17], v[208:211], v[174:177], v[2:17]
	ds_read_b64_tr_b16 v[166:167], v145 offset:33792
	ds_read_b64_tr_b16 v[168:169], v145 offset:35840
	s_waitcnt lgkmcnt(10)
	v_mfma_f32_32x32x16_bf16 v[2:17], v[216:219], v[178:181], v[2:17]
	ds_read_b64_tr_b16 v[170:171], v145 offset:37888
	ds_read_b64_tr_b16 v[172:173], v145 offset:39936
	v_exp_f32_e32 v66, v66
	v_exp_f32_e32 v67, v67
	v_exp_f32_e32 v68, v68
	s_waitcnt lgkmcnt(10)
	v_mfma_f32_32x32x16_bf16 v[18:33], v[192:195], v[224:227], v[18:33]
	ds_read_b64_tr_b16 v[174:175], v145 offset:41984
	ds_read_b64_tr_b16 v[176:177], v145 offset:44032
	v_exp_f32_e32 v69, v69
	v_exp_f32_e32 v70, v70
	s_waitcnt lgkmcnt(10)
	v_mfma_f32_32x32x16_bf16 v[18:33], v[200:203], v[228:231], v[18:33]
	ds_read_b64_tr_b16 v[178:179], v145 offset:46080
	ds_read_b64_tr_b16 v[180:181], v145 offset:48128
	v_exp_f32_e32 v71, v71
	v_exp_f32_e32 v72, v72
	v_exp_f32_e32 v73, v73
	s_waitcnt lgkmcnt(10)
	v_mfma_f32_32x32x16_bf16 v[18:33], v[208:211], v[232:235], v[18:33]
	ds_read_b64_tr_b16 v[224:225], v145 offset:34304
	ds_read_b64_tr_b16 v[226:227], v145 offset:36352
	v_exp_f32_e32 v74, v74
	v_exp_f32_e32 v75, v75
	s_waitcnt lgkmcnt(10)
	v_mfma_f32_32x32x16_bf16 v[18:33], v[216:219], v[236:239], v[18:33]
	ds_read_b64_tr_b16 v[228:229], v145 offset:38400
	ds_read_b64_tr_b16 v[230:231], v145 offset:40448
	v_exp_f32_e32 v76, v76
	v_exp_f32_e32 v77, v77
	v_exp_f32_e32 v78, v78
	s_waitcnt lgkmcnt(10)
	v_mfma_f32_32x32x16_bf16 v[34:49], v[192:195], v[166:169], v[34:49]
	ds_read_b64_tr_b16 v[232:233], v145 offset:42496
	ds_read_b64_tr_b16 v[234:235], v145 offset:44544
	ds_read_b128 v[166:169], v240 offset:49152
	v_exp_f32_e32 v79, v79
	v_exp_f32_e32 v80, v80
	s_waitcnt lgkmcnt(11)
	v_mfma_f32_32x32x16_bf16 v[34:49], v[200:203], v[170:173], v[34:49]
	ds_read_b64_tr_b16 v[236:237], v145 offset:46592
	ds_read_b64_tr_b16 v[238:239], v145 offset:48640
	ds_read_b128 v[170:173], v240 offset:57344
	v_exp_f32_e32 v81, v81
	v_exp_f32_e32 v82, v82
	v_exp_f32_e32 v83, v83
	s_waitcnt lgkmcnt(12)
	v_mfma_f32_32x32x16_bf16 v[34:49], v[208:211], v[174:177], v[34:49]
	ds_read_b128 v[174:177], v241 offset:49152
	v_exp_f32_e32 v84, v84
	v_exp_f32_e32 v85, v85
	s_waitcnt lgkmcnt(11)
	v_mfma_f32_32x32x16_bf16 v[34:49], v[216:219], v[178:181], v[34:49]
	ds_read_b128 v[178:181], v241 offset:57344
	v_exp_f32_e32 v86, v86
	v_exp_f32_e32 v87, v87
	v_exp_f32_e32 v88, v88
	s_waitcnt lgkmcnt(10)
	v_mfma_f32_32x32x16_bf16 v[50:65], v[192:195], v[224:227], v[50:65]
	ds_read_b128 v[224:227], v242 offset:49152
	v_exp_f32_e32 v89, v89
	v_exp_f32_e32 v90, v90
	s_waitcnt lgkmcnt(9)
	v_mfma_f32_32x32x16_bf16 v[50:65], v[200:203], v[228:231], v[50:65]
	ds_read_b128 v[228:231], v242 offset:57344
	v_exp_f32_e32 v91, v91
	v_exp_f32_e32 v92, v92
	v_exp_f32_e32 v93, v93
	s_waitcnt lgkmcnt(8)
	v_mfma_f32_32x32x16_bf16 v[50:65], v[208:211], v[232:235], v[50:65]
	ds_read_b128 v[232:235], v243 offset:49152
	v_exp_f32_e32 v94, v94
	v_exp_f32_e32 v95, v95
	s_waitcnt lgkmcnt(6)
	v_mfma_f32_32x32x16_bf16 v[50:65], v[216:219], v[236:239], v[50:65]
	ds_read_b128 v[236:239], v243 offset:57344
	v_exp_f32_e32 v96, v96
	v_exp_f32_e32 v97, v97
	s_waitcnt vmcnt(0)
	s_barrier
	v_mfma_f32_32x32x16_bf16 v[192:207], v[166:169], v[106:109], 0
	v_add_f32_e32 v131, v66, v67
	v_add_f32_e32 v132, v68, v69
	v_add_f32_e32 v131, v70, v131
	s_waitcnt lgkmcnt(6)
	v_mfma_f32_32x32x16_bf16 v[208:223], v[170:173], v[106:109], 0
	v_add_f32_e32 v132, v71, v132
	v_add_f32_e32 v131, v72, v131
	v_add_f32_e32 v132, v73, v132
	ds_read_b128 v[166:169], v244 offset:49152
	ds_read_b128 v[170:173], v244 offset:57344
	s_waitcnt lgkmcnt(7)
	v_mfma_f32_32x32x16_bf16 v[192:207], v[174:177], v[102:105], v[192:207]
	v_add_f32_e32 v131, v74, v131
	v_add_f32_e32 v132, v75, v132
	v_add_f32_e32 v131, v76, v131
	s_waitcnt lgkmcnt(6)
	v_mfma_f32_32x32x16_bf16 v[208:223], v[178:181], v[102:105], v[208:223]
	v_add_f32_e32 v132, v77, v132
	v_add_f32_e32 v131, v78, v131
	v_add_f32_e32 v132, v79, v132
	ds_read_b128 v[174:177], v245 offset:49152
	ds_read_b128 v[178:181], v245 offset:57344
	s_waitcnt lgkmcnt(7)
	v_mfma_f32_32x32x16_bf16 v[192:207], v[224:227], v[98:101], v[192:207]
	v_add_f32_e32 v131, v80, v131
	v_add_f32_e32 v132, v81, v132
	v_add_f32_e32 v131, v82, v131
	s_waitcnt lgkmcnt(6)
	v_mfma_f32_32x32x16_bf16 v[208:223], v[228:231], v[98:101], v[208:223]
	v_add_f32_e32 v132, v83, v132
	v_add_f32_e32 v131, v84, v131
	v_add_f32_e32 v132, v85, v132
	ds_read_b128 v[224:227], v246 offset:49152
	ds_read_b128 v[228:231], v246 offset:57344
	s_waitcnt lgkmcnt(7)
	v_mfma_f32_32x32x16_bf16 v[192:207], v[232:235], v[126:129], v[192:207]
	v_add_f32_e32 v131, v86, v131
	v_add_f32_e32 v132, v87, v132
	v_add_f32_e32 v131, v88, v131
	s_waitcnt lgkmcnt(6)
	v_mfma_f32_32x32x16_bf16 v[208:223], v[236:239], v[126:129], v[208:223]
	v_add_f32_e32 v132, v89, v132
	v_add_f32_e32 v131, v90, v131
	v_add_f32_e32 v132, v91, v132
	ds_read_b128 v[232:235], v247 offset:49152
	ds_read_b128 v[236:239], v247 offset:57344
	s_waitcnt lgkmcnt(7)
	v_mfma_f32_32x32x16_bf16 v[192:207], v[166:169], v[122:125], v[192:207]
	v_add_f32_e32 v131, v92, v131
	v_add_f32_e32 v132, v93, v132
	v_add_f32_e32 v131, v94, v131
	s_waitcnt lgkmcnt(6)
	v_mfma_f32_32x32x16_bf16 v[208:223], v[170:173], v[122:125], v[208:223]
	v_add_f32_e32 v132, v95, v132
	v_add_f32_e32 v131, v96, v131
	v_add_f32_e32 v132, v97, v132
	ds_read_b64_tr_b16 v[166:167], v130 offset:0
	ds_read_b64_tr_b16 v[168:169], v130 offset:2048
	ds_read_b64_tr_b16 v[170:171], v130 offset:4096
	ds_read_b64_tr_b16 v[172:173], v130 offset:6144
	s_waitcnt lgkmcnt(9)
	v_mfma_f32_32x32x16_bf16 v[192:207], v[174:177], v[118:121], v[192:207]
	v_add_f32_e32 v131, v131, v132
	v_add_f32_e32 v165, v165, v131
	v_cvt_pk_bf16_f32 v66, v66, v67
	s_waitcnt lgkmcnt(8)
	v_mfma_f32_32x32x16_bf16 v[208:223], v[178:181], v[118:121], v[208:223]
	v_cvt_pk_bf16_f32 v67, v68, v69
	v_cvt_pk_bf16_f32 v68, v70, v71
	v_cvt_pk_bf16_f32 v69, v72, v73
	ds_read_b64_tr_b16 v[174:175], v130 offset:8192
	ds_read_b64_tr_b16 v[176:177], v130 offset:10240
	ds_read_b64_tr_b16 v[178:179], v130 offset:12288
	ds_read_b64_tr_b16 v[180:181], v130 offset:14336
	s_waitcnt lgkmcnt(11)
	v_mfma_f32_32x32x16_bf16 v[192:207], v[224:227], v[114:117], v[192:207]
	v_cvt_pk_bf16_f32 v74, v74, v75
	v_cvt_pk_bf16_f32 v75, v76, v77
	v_cvt_pk_bf16_f32 v76, v78, v79
	s_waitcnt lgkmcnt(10)
	v_mfma_f32_32x32x16_bf16 v[208:223], v[228:231], v[114:117], v[208:223]
	v_cvt_pk_bf16_f32 v77, v80, v81
	v_cvt_pk_bf16_f32 v82, v82, v83
	v_cvt_pk_bf16_f32 v83, v84, v85
	ds_read_b64_tr_b16 v[224:225], v130 offset:512
	ds_read_b64_tr_b16 v[226:227], v130 offset:2560
	ds_read_b64_tr_b16 v[228:229], v130 offset:4608
	ds_read_b64_tr_b16 v[230:231], v130 offset:6656
	s_waitcnt lgkmcnt(13)
	v_mfma_f32_32x32x16_bf16 v[192:207], v[232:235], v[110:113], v[192:207]
	v_cvt_pk_bf16_f32 v84, v86, v87
	v_cvt_pk_bf16_f32 v85, v88, v89
	v_cvt_pk_bf16_f32 v90, v90, v91
	s_waitcnt lgkmcnt(12)
	v_mfma_f32_32x32x16_bf16 v[208:223], v[236:239], v[110:113], v[208:223]
	v_cvt_pk_bf16_f32 v91, v92, v93
	v_cvt_pk_bf16_f32 v92, v94, v95
	v_cvt_pk_bf16_f32 v93, v96, v97
	s_waitcnt lgkmcnt(10)
	v_mfma_f32_32x32x16_bf16 v[2:17], v[66:69], v[166:169], v[2:17]
	ds_read_b64_tr_b16 v[232:233], v130 offset:8704
	ds_read_b64_tr_b16 v[234:235], v130 offset:10752
	s_waitcnt lgkmcnt(10)
	v_mfma_f32_32x32x16_bf16 v[2:17], v[74:77], v[170:173], v[2:17]
	ds_read_b64_tr_b16 v[236:237], v130 offset:12800
	ds_read_b64_tr_b16 v[238:239], v130 offset:14848
	s_waitcnt lgkmcnt(10)
	v_mfma_f32_32x32x16_bf16 v[2:17], v[82:85], v[174:177], v[2:17]
	ds_read_b64_tr_b16 v[166:167], v130 offset:1024
	ds_read_b64_tr_b16 v[168:169], v130 offset:3072
	s_waitcnt lgkmcnt(10)
	v_mfma_f32_32x32x16_bf16 v[2:17], v[90:93], v[178:181], v[2:17]
	ds_read_b64_tr_b16 v[170:171], v130 offset:5120
	ds_read_b64_tr_b16 v[172:173], v130 offset:7168
	v_exp_f32_e32 v192, v192
	v_exp_f32_e32 v193, v193
	v_exp_f32_e32 v194, v194
	s_waitcnt lgkmcnt(10)
	v_mfma_f32_32x32x16_bf16 v[18:33], v[66:69], v[224:227], v[18:33]
	ds_read_b64_tr_b16 v[174:175], v130 offset:9216
	ds_read_b64_tr_b16 v[176:177], v130 offset:11264
	v_exp_f32_e32 v195, v195
	v_exp_f32_e32 v196, v196
	s_waitcnt lgkmcnt(10)
	v_mfma_f32_32x32x16_bf16 v[18:33], v[74:77], v[228:231], v[18:33]
	ds_read_b64_tr_b16 v[178:179], v130 offset:13312
	ds_read_b64_tr_b16 v[180:181], v130 offset:15360
	v_exp_f32_e32 v197, v197
	v_exp_f32_e32 v198, v198
	v_exp_f32_e32 v199, v199
	s_waitcnt lgkmcnt(10)
	v_mfma_f32_32x32x16_bf16 v[18:33], v[82:85], v[232:235], v[18:33]
	ds_read_b64_tr_b16 v[224:225], v130 offset:1536
	ds_read_b64_tr_b16 v[226:227], v130 offset:3584
	v_exp_f32_e32 v200, v200
	v_exp_f32_e32 v201, v201
	s_waitcnt lgkmcnt(10)
	v_mfma_f32_32x32x16_bf16 v[18:33], v[90:93], v[236:239], v[18:33]
	ds_read_b64_tr_b16 v[228:229], v130 offset:5632
	ds_read_b64_tr_b16 v[230:231], v130 offset:7680
	v_exp_f32_e32 v202, v202
	v_exp_f32_e32 v203, v203
	v_exp_f32_e32 v204, v204
	s_waitcnt lgkmcnt(10)
	v_mfma_f32_32x32x16_bf16 v[34:49], v[66:69], v[166:169], v[34:49]
	ds_read_b64_tr_b16 v[232:233], v130 offset:9728
	ds_read_b64_tr_b16 v[234:235], v130 offset:11776
	v_exp_f32_e32 v205, v205
	v_exp_f32_e32 v206, v206
	s_waitcnt lgkmcnt(10)
	v_mfma_f32_32x32x16_bf16 v[34:49], v[74:77], v[170:173], v[34:49]
	ds_read_b64_tr_b16 v[236:237], v130 offset:13824
	ds_read_b64_tr_b16 v[238:239], v130 offset:15872
	v_exp_f32_e32 v207, v207
	v_exp_f32_e32 v208, v208
	v_exp_f32_e32 v209, v209
	s_waitcnt lgkmcnt(10)
	v_mfma_f32_32x32x16_bf16 v[34:49], v[82:85], v[174:177], v[34:49]
	v_exp_f32_e32 v210, v210
	v_exp_f32_e32 v211, v211
	s_waitcnt lgkmcnt(8)
	v_mfma_f32_32x32x16_bf16 v[34:49], v[90:93], v[178:181], v[34:49]
	v_exp_f32_e32 v212, v212
	v_exp_f32_e32 v213, v213
	v_exp_f32_e32 v214, v214
	s_waitcnt lgkmcnt(6)
	v_mfma_f32_32x32x16_bf16 v[50:65], v[66:69], v[224:227], v[50:65]
	v_exp_f32_e32 v215, v215
	v_exp_f32_e32 v216, v216
	s_waitcnt lgkmcnt(4)
	v_mfma_f32_32x32x16_bf16 v[50:65], v[74:77], v[228:231], v[50:65]
	v_exp_f32_e32 v217, v217
	v_exp_f32_e32 v218, v218
	v_exp_f32_e32 v219, v219
	s_waitcnt lgkmcnt(2)
	v_mfma_f32_32x32x16_bf16 v[50:65], v[82:85], v[232:235], v[50:65]
	v_exp_f32_e32 v220, v220
	v_exp_f32_e32 v221, v221
	s_waitcnt lgkmcnt(0)
	v_mfma_f32_32x32x16_bf16 v[50:65], v[90:93], v[236:239], v[50:65]
	v_exp_f32_e32 v222, v222
	v_exp_f32_e32 v223, v223
	s_waitcnt vmcnt(0)
	s_barrier
	ds_read_b64_tr_b16 v[166:167], v130 offset:32768
	ds_read_b64_tr_b16 v[168:169], v130 offset:34816
	ds_read_b64_tr_b16 v[170:171], v130 offset:36864
	ds_read_b64_tr_b16 v[172:173], v130 offset:38912
	ds_read_b64_tr_b16 v[174:175], v130 offset:40960
	ds_read_b64_tr_b16 v[176:177], v130 offset:43008
	ds_read_b64_tr_b16 v[178:179], v130 offset:45056
	ds_read_b64_tr_b16 v[180:181], v130 offset:47104
	ds_read_b64_tr_b16 v[224:225], v130 offset:33280
	ds_read_b64_tr_b16 v[226:227], v130 offset:35328
	ds_read_b64_tr_b16 v[228:229], v130 offset:37376
	ds_read_b64_tr_b16 v[230:231], v130 offset:39424
	v_add_f32_e32 v131, v192, v193
	v_add_f32_e32 v132, v194, v195
	v_add_f32_e32 v131, v196, v131
	v_add_f32_e32 v132, v197, v132
	v_add_f32_e32 v131, v198, v131
	v_add_f32_e32 v132, v199, v132
	v_add_f32_e32 v131, v200, v131
	v_add_f32_e32 v132, v201, v132
	v_add_f32_e32 v131, v202, v131
	v_add_f32_e32 v132, v203, v132
	v_add_f32_e32 v131, v204, v131
	v_add_f32_e32 v132, v205, v132
	v_add_f32_e32 v131, v206, v131
	v_add_f32_e32 v132, v207, v132
	v_add_f32_e32 v131, v208, v131
	v_add_f32_e32 v132, v209, v132
	v_add_f32_e32 v131, v210, v131
	v_add_f32_e32 v132, v211, v132
	v_add_f32_e32 v131, v212, v131
	v_add_f32_e32 v132, v213, v132
	v_add_f32_e32 v131, v214, v131
	v_add_f32_e32 v132, v215, v132
	v_add_f32_e32 v131, v216, v131
	v_add_f32_e32 v132, v217, v132
	v_add_f32_e32 v131, v218, v131
	v_add_f32_e32 v132, v219, v132
	v_add_f32_e32 v131, v220, v131
	v_add_f32_e32 v132, v221, v132
	v_add_f32_e32 v131, v222, v131
	v_add_f32_e32 v132, v223, v132
	v_add_f32_e32 v131, v131, v132
	v_add_f32_e32 v165, v165, v131
	v_cvt_pk_bf16_f32 v192, v192, v193
	v_cvt_pk_bf16_f32 v193, v194, v195
	v_cvt_pk_bf16_f32 v194, v196, v197
	v_cvt_pk_bf16_f32 v195, v198, v199
	v_cvt_pk_bf16_f32 v200, v200, v201
	v_cvt_pk_bf16_f32 v201, v202, v203
	v_cvt_pk_bf16_f32 v202, v204, v205
	v_cvt_pk_bf16_f32 v203, v206, v207
	v_cvt_pk_bf16_f32 v208, v208, v209
	v_cvt_pk_bf16_f32 v209, v210, v211
	v_cvt_pk_bf16_f32 v210, v212, v213
	v_cvt_pk_bf16_f32 v211, v214, v215
	v_cvt_pk_bf16_f32 v216, v216, v217
	v_cvt_pk_bf16_f32 v217, v218, v219
	v_cvt_pk_bf16_f32 v218, v220, v221
	v_cvt_pk_bf16_f32 v219, v222, v223
	s_waitcnt lgkmcnt(10)
	v_mfma_f32_32x32x16_bf16 v[2:17], v[192:195], v[166:169], v[2:17]
	ds_read_b64_tr_b16 v[232:233], v130 offset:41472
	ds_read_b64_tr_b16 v[234:235], v130 offset:43520
	s_waitcnt lgkmcnt(10)
	v_mfma_f32_32x32x16_bf16 v[2:17], v[200:203], v[170:173], v[2:17]
	ds_read_b64_tr_b16 v[236:237], v130 offset:45568
	ds_read_b64_tr_b16 v[238:239], v130 offset:47616
	s_waitcnt lgkmcnt(10)
	v_mfma_f32_32x32x16_bf16 v[2:17], v[208:211], v[174:177], v[2:17]
	ds_read_b64_tr_b16 v[166:167], v130 offset:33792
	ds_read_b64_tr_b16 v[168:169], v130 offset:35840
	s_waitcnt lgkmcnt(10)
	v_mfma_f32_32x32x16_bf16 v[2:17], v[216:219], v[178:181], v[2:17]
	ds_read_b64_tr_b16 v[170:171], v130 offset:37888
	ds_read_b64_tr_b16 v[172:173], v130 offset:39936
	s_waitcnt lgkmcnt(10)
	v_mfma_f32_32x32x16_bf16 v[18:33], v[192:195], v[224:227], v[18:33]
	ds_read_b64_tr_b16 v[174:175], v130 offset:41984
	ds_read_b64_tr_b16 v[176:177], v130 offset:44032
	s_waitcnt lgkmcnt(10)
	v_mfma_f32_32x32x16_bf16 v[18:33], v[200:203], v[228:231], v[18:33]
	ds_read_b64_tr_b16 v[178:179], v130 offset:46080
	ds_read_b64_tr_b16 v[180:181], v130 offset:48128
	s_waitcnt lgkmcnt(10)
	v_mfma_f32_32x32x16_bf16 v[18:33], v[208:211], v[232:235], v[18:33]
	ds_read_b64_tr_b16 v[224:225], v130 offset:34304
	ds_read_b64_tr_b16 v[226:227], v130 offset:36352
	s_waitcnt lgkmcnt(10)
	v_mfma_f32_32x32x16_bf16 v[18:33], v[216:219], v[236:239], v[18:33]
	ds_read_b64_tr_b16 v[228:229], v130 offset:38400
	ds_read_b64_tr_b16 v[230:231], v130 offset:40448
	s_waitcnt lgkmcnt(10)
	v_mfma_f32_32x32x16_bf16 v[34:49], v[192:195], v[166:169], v[34:49]
	ds_read_b64_tr_b16 v[232:233], v130 offset:42496
	ds_read_b64_tr_b16 v[234:235], v130 offset:44544
	s_waitcnt lgkmcnt(10)
	v_mfma_f32_32x32x16_bf16 v[34:49], v[200:203], v[170:173], v[34:49]
	ds_read_b64_tr_b16 v[236:237], v130 offset:46592
	ds_read_b64_tr_b16 v[238:239], v130 offset:48640
	s_waitcnt lgkmcnt(10)
	v_mfma_f32_32x32x16_bf16 v[34:49], v[208:211], v[174:177], v[34:49]
	s_waitcnt lgkmcnt(8)
	v_mfma_f32_32x32x16_bf16 v[34:49], v[216:219], v[178:181], v[34:49]
	s_waitcnt lgkmcnt(6)
	v_mfma_f32_32x32x16_bf16 v[50:65], v[192:195], v[224:227], v[50:65]
	s_waitcnt lgkmcnt(4)
	v_mfma_f32_32x32x16_bf16 v[50:65], v[200:203], v[228:231], v[50:65]
	s_waitcnt lgkmcnt(2)
	v_mfma_f32_32x32x16_bf16 v[50:65], v[208:211], v[232:235], v[50:65]
	s_waitcnt lgkmcnt(0)
	v_mfma_f32_32x32x16_bf16 v[50:65], v[216:219], v[236:239], v[50:65]
	v_mov_b32_e32 v132, v165
	s_nop 7
	v_permlane32_swap_b32_e32 v165, v132
	s_nop 1
	v_add_f32_e32 v165, v165, v132
	s_nop 7
	s_and_saveexec_b64 s[18:19], vcc
	v_lshl_add_u32 v68, v144, 2, s44
	ds_write_b32 v68, v165
	s_branch .LBB0_418

	.amdhsa_kernel _Z5k_all6Paramsii
		.amdhsa_group_segment_fixed_size 0
		.amdhsa_private_segment_fixed_size 0
		.amdhsa_kernarg_size 416
		.amdhsa_user_sgpr_count 2
		.amdhsa_user_sgpr_dispatch_ptr 0
		.amdhsa_user_sgpr_queue_ptr 0
		.amdhsa_user_sgpr_kernarg_segment_ptr 1
		.amdhsa_user_sgpr_dispatch_id 0
		.amdhsa_user_sgpr_kernarg_preload_length 0
		.amdhsa_user_sgpr_kernarg_preload_offset 0
		.amdhsa_user_sgpr_private_segment_size 0
		.amdhsa_uses_dynamic_stack 0
		.amdhsa_enable_private_segment 0
		.amdhsa_system_sgpr_workgroup_id_x 1
		.amdhsa_system_sgpr_workgroup_id_y 0
		.amdhsa_system_sgpr_workgroup_id_z 0
		.amdhsa_system_sgpr_workgroup_info 0
		.amdhsa_system_vgpr_workitem_id 2
		.amdhsa_next_free_vgpr 255
		.amdhsa_next_free_sgpr 102
		.amdhsa_accum_offset 256
		.amdhsa_reserve_vcc 1
		.amdhsa_float_round_mode_32 0
		.amdhsa_float_round_mode_16_64 0
		.amdhsa_float_denorm_mode_32 3
		.amdhsa_float_denorm_mode_16_64 3
		.amdhsa_dx10_clamp 1
		.amdhsa_ieee_mode 1
		.amdhsa_fp16_overflow 0
		.amdhsa_tg_split 0
		.amdhsa_exception_fp_ieee_invalid_op 0
		.amdhsa_exception_fp_denorm_src 0
		.amdhsa_exception_fp_ieee_div_zero 0
		.amdhsa_exception_fp_ieee_overflow 0
		.amdhsa_exception_fp_ieee_underflow 0
		.amdhsa_exception_fp_ieee_inexact 0
		.amdhsa_exception_int_div_zero 0
	.end_amdhsa_kernel

amdhsa.kernels:
  - .agpr_count:     0
    .args:
      - .offset:         0
        .size:           152
        .value_kind:     by_value
      - .offset:         152
        .size:           4
        .value_kind:     by_value
      - .offset:         156
        .size:           4
        .value_kind:     by_value
      - .offset:         160
        .size:           4
        .value_kind:     hidden_block_count_x
      - .offset:         164
        .size:           4
        .value_kind:     hidden_block_count_y
      - .offset:         168
        .size:           4
        .value_kind:     hidden_block_count_z
      - .offset:         172
        .size:           2
        .value_kind:     hidden_group_size_x
      - .offset:         174
        .size:           2
        .value_kind:     hidden_group_size_y
      - .offset:         176
        .size:           2
        .value_kind:     hidden_group_size_z
      - .offset:         178
        .size:           2
        .value_kind:     hidden_remainder_x
      - .offset:         180
        .size:           2
        .value_kind:     hidden_remainder_y
      - .offset:         182
        .size:           2
        .value_kind:     hidden_remainder_z
      - .offset:         200
        .size:           8
        .value_kind:     hidden_global_offset_x
      - .offset:         208
        .size:           8
        .value_kind:     hidden_global_offset_y
      - .offset:         216
        .size:           8
        .value_kind:     hidden_global_offset_z
      - .offset:         224
        .size:           2
        .value_kind:     hidden_grid_dims
      - .offset:         248
        .size:           8
        .value_kind:     hidden_multigrid_sync_arg
      - .offset:         280
        .size:           4
        .value_kind:     hidden_dynamic_lds_size
    .group_segment_fixed_size: 0
    .kernarg_segment_align: 8
    .kernarg_segment_size: 416
    .language:       OpenCL C
    .language_version:
      - 2
      - 0
    .max_flat_workgroup_size: 512
    .name:           _Z5k_all6Paramsii
    .private_segment_fixed_size: 0
    .sgpr_count:     108
    .sgpr_spill_count: 8
    .symbol:         _Z5k_all6Paramsii.kd
    .uniform_work_group_size: 1
    .uses_dynamic_stack: false
    .vgpr_count:     255
    .vgpr_spill_count: 0
    .wavefront_size: 64
